# wave-level 64x64 transposes (V^T, (x dt)^T, B^T): 32 row loads in flight per half-batch instead of 2 (kept under the 63-op vmcnt limit); conv taps batched
# speedup vs baseline: 1.0229x; 1.0103x over previous
; __device__ __forceinline__ float bf2f(unsigned v) { return __uint_as_float(v << 16); }
; __device__ __forceinline__ int row_of_pos(int b, int pos) { return (pos < CTXL) ? MLAT + b * CTXL + pos : b * SEQ + (pos - CTXL); }
; template <bool SRC_BF16> __device__ __forceinline__ void tr_tile(const void* src, int stride, int col0, int myrow, float myscale, bf16_t* dst, float* wl, int lane) {
;     float* scr = wl; int* rws = (int*)(wl + 64 * 65); float* scs = wl + 64 * 65 + 64;
;     rws[lane] = myrow; scs[lane] = myscale;
;     asm volatile("s_waitcnt lgkmcnt(0)" ::: "memory");
; #pragma unroll 32
;     for (int i = 0; i < 64; ++i) { const int r = rws[i]; float v;
;         if (SRC_BF16) v = bf2f(((const bf16_t*)src)[(size_t)r * stride + col0 + lane]); else v = ((const float*)src)[(size_t)r * stride + col0 + lane] * scs[i];
;         scr[i * 65 + lane] = v; }
; __device__ __forceinline__ void prep_phase(const Args& a, int l, float* lds) {
;     ...
;       for (int tI = gw; tI < 16 * 2 * 68; tI += NGW) { const int pt = tI % 68, rest = tI / 68, dh = rest & 1, bh = rest >> 1, b = bh >> 3, h = bh & 7;
;           tr_tile<true>(P, NINP, VOFF + h * 128 + 64 * dh, row_of_pos(b, 64 * pt + lane), 1.f, Vt + ((size_t)bh * 128 + 64 * dh) * KVL + 64 * pt, wl, lane); } }
.LBB0_235:
	s_or_b64 exec, exec, s[6:7]
	v_ashrrev_i32_e32 v20, 1, v5
	v_lshlrev_b32_e32 v5, 6, v5
	v_lshlrev_b32_e32 v9, 7, v20
	v_and_b32_e32 v11, 64, v5
	s_movk_i32 s6, 0x380
	ds_write2st64_b32 v25, v7, v195 offset0:65 offset1:66
	v_and_or_b32 v5, v9, s6, v11
	s_waitcnt lgkmcnt(0)
	v_add_u32_e32 v18, v29, v0
	v_lshlrev_b32_e32 v0, 1, v5
	ds_read_b128 v[30:33], v24 offset:16640
	ds_read_b128 v[34:37], v24 offset:16656
	v_lshl_add_u64 v[22:23], s[96:97], 0, v[0:1]
	v_mov_b32_e32 v5, v1
	v_lshl_add_u64 v[22:23], v[22:23], 0, v[4:5]
	s_mov_b64 s[6:7], 0x1000
	v_lshl_add_u64 v[22:23], v[22:23], 0, s[6:7]
	s_waitcnt lgkmcnt(0)
	v_mad_i64_i32 v[38:39], s[6:7], v30, s79, v[22:23]
	v_mad_i64_i32 v[30:31], s[6:7], v31, s79, v[22:23]
	global_load_ushort v66, v[38:39], off
	global_load_ushort v67, v[30:31], off
	v_mad_i64_i32 v[30:31], s[6:7], v32, s79, v[22:23]
	v_mad_i64_i32 v[32:33], s[6:7], v33, s79, v[22:23]
	v_ashrrev_i32_e32 v21, 31, v20
	v_lshlrev_b64 v[20:21], 7, v[20:21]
	v_or_b32_e32 v0, v20, v11
	v_ashrrev_i32_e32 v19, 31, v18
	v_mov_b32_e32 v11, v1
	v_mov_b32_e32 v13, v1
	v_mov_b32_e32 v15, v1
	v_mov_b32_e32 v17, v1
	v_add_u32_e32 v3, s44, v3
	v_add_u32_e32 v29, s8, v29
	global_load_ushort v68, v[30:31], off
	global_load_ushort v69, v[32:33], off
	s_waitcnt lgkmcnt(0)
	v_mad_i64_i32 v[30:31], s[6:7], v34, s79, v[22:23]
	v_mad_i64_i32 v[32:33], s[6:7], v35, s79, v[22:23]
	global_load_ushort v70, v[30:31], off
	global_load_ushort v71, v[32:33], off
	v_mad_i64_i32 v[30:31], s[6:7], v36, s79, v[22:23]
	v_mad_i64_i32 v[32:33], s[6:7], v37, s79, v[22:23]
	global_load_ushort v72, v[30:31], off
	global_load_ushort v73, v[32:33], off
	ds_read_b128 v[30:33], v24 offset:16672
	ds_read_b128 v[34:37], v24 offset:16688
	s_waitcnt lgkmcnt(0)
	v_mad_i64_i32 v[38:39], s[6:7], v30, s79, v[22:23]
	v_mad_i64_i32 v[30:31], s[6:7], v31, s79, v[22:23]
	global_load_ushort v74, v[38:39], off
	global_load_ushort v75, v[30:31], off
	v_mad_i64_i32 v[30:31], s[6:7], v32, s79, v[22:23]
	v_mad_i64_i32 v[32:33], s[6:7], v33, s79, v[22:23]
	global_load_ushort v76, v[30:31], off
	global_load_ushort v77, v[32:33], off
	s_waitcnt lgkmcnt(0)
	v_mad_i64_i32 v[30:31], s[6:7], v34, s79, v[22:23]
	v_mad_i64_i32 v[32:33], s[6:7], v35, s79, v[22:23]
	global_load_ushort v78, v[30:31], off
	global_load_ushort v79, v[32:33], off
	v_mad_i64_i32 v[30:31], s[6:7], v36, s79, v[22:23]
	v_mad_i64_i32 v[32:33], s[6:7], v37, s79, v[22:23]
	global_load_ushort v80, v[30:31], off
	global_load_ushort v81, v[32:33], off
	ds_read_b128 v[30:33], v24 offset:16704
	ds_read_b128 v[34:37], v24 offset:16720
	s_waitcnt lgkmcnt(0)
	v_mad_i64_i32 v[38:39], s[6:7], v30, s79, v[22:23]
	v_mad_i64_i32 v[30:31], s[6:7], v31, s79, v[22:23]
	global_load_ushort v82, v[38:39], off
	global_load_ushort v83, v[30:31], off
	v_mad_i64_i32 v[30:31], s[6:7], v32, s79, v[22:23]
	v_mad_i64_i32 v[32:33], s[6:7], v33, s79, v[22:23]
	global_load_ushort v84, v[30:31], off
	global_load_ushort v85, v[32:33], off
	s_waitcnt lgkmcnt(0)
	v_mad_i64_i32 v[30:31], s[6:7], v34, s79, v[22:23]
	v_mad_i64_i32 v[32:33], s[6:7], v35, s79, v[22:23]
	global_load_ushort v86, v[30:31], off
	global_load_ushort v87, v[32:33], off
	v_mad_i64_i32 v[30:31], s[6:7], v36, s79, v[22:23]
	v_mad_i64_i32 v[32:33], s[6:7], v37, s79, v[22:23]
	global_load_ushort v88, v[30:31], off
	global_load_ushort v89, v[32:33], off
	ds_read_b128 v[30:33], v24 offset:16736
	s_waitcnt lgkmcnt(0)
	v_mad_i64_i32 v[34:35], s[6:7], v30, s79, v[22:23]
	v_mad_i64_i32 v[30:31], s[6:7], v31, s79, v[22:23]
	global_load_ushort v90, v[34:35], off
	global_load_ushort v91, v[30:31], off
	v_mad_i64_i32 v[30:31], s[6:7], v32, s79, v[22:23]
	v_mad_i64_i32 v[32:33], s[6:7], v33, s79, v[22:23]
	global_load_ushort v92, v[30:31], off
	global_load_ushort v93, v[32:33], off
	ds_read_b128 v[30:33], v24 offset:16752
	s_waitcnt lgkmcnt(0)
	v_mad_i64_i32 v[34:35], s[6:7], v30, s79, v[22:23]
	v_mad_i64_i32 v[30:31], s[6:7], v31, s79, v[22:23]
	global_load_ushort v94, v[34:35], off
	global_load_ushort v95, v[30:31], off
	v_mad_i64_i32 v[30:31], s[6:7], v32, s79, v[22:23]
	v_mad_i64_i32 v[32:33], s[6:7], v33, s79, v[22:23]
	global_load_ushort v96, v[30:31], off
	global_load_ushort v97, v[32:33], off
	ds_read_b128 v[30:33], v24 offset:16768
	s_waitcnt lgkmcnt(0)
	v_mad_i64_i32 v[34:35], s[6:7], v30, s79, v[22:23]
	v_mad_i64_i32 v[30:31], s[6:7], v31, s79, v[22:23]
	s_waitcnt vmcnt(28)
	v_lshlrev_b32_e32 v66, 16, v66
	v_lshlrev_b32_e32 v67, 16, v67
	v_lshlrev_b32_e32 v68, 16, v68
	v_lshlrev_b32_e32 v69, 16, v69
	ds_write_b32 v25, v66 offset:0
	ds_write_b32 v25, v67 offset:260
	ds_write_b32 v25, v68 offset:520
	ds_write_b32 v25, v69 offset:780
	s_waitcnt vmcnt(24)
	v_lshlrev_b32_e32 v70, 16, v70
	v_lshlrev_b32_e32 v71, 16, v71
	v_lshlrev_b32_e32 v72, 16, v72
	v_lshlrev_b32_e32 v73, 16, v73
	ds_write_b32 v25, v70 offset:1040
	ds_write_b32 v25, v71 offset:1300
	ds_write_b32 v25, v72 offset:1560
	ds_write_b32 v25, v73 offset:1820
	s_waitcnt vmcnt(20)
	v_lshlrev_b32_e32 v74, 16, v74
	v_lshlrev_b32_e32 v75, 16, v75
	v_lshlrev_b32_e32 v76, 16, v76
	v_lshlrev_b32_e32 v77, 16, v77
	ds_write_b32 v25, v74 offset:2080
	ds_write_b32 v25, v75 offset:2340
	ds_write_b32 v25, v76 offset:2600
	ds_write_b32 v25, v77 offset:2860
	s_waitcnt vmcnt(16)
	v_lshlrev_b32_e32 v78, 16, v78
	v_lshlrev_b32_e32 v79, 16, v79
	v_lshlrev_b32_e32 v80, 16, v80
	v_lshlrev_b32_e32 v81, 16, v81
	ds_write_b32 v25, v78 offset:3120
	ds_write_b32 v25, v79 offset:3380
	ds_write_b32 v25, v80 offset:3640
	ds_write_b32 v25, v81 offset:3900
	s_waitcnt vmcnt(12)
; __device__ __forceinline__ float bf2f(unsigned v) { return __uint_as_float(v << 16); }
; template <bool SRC_BF16> __device__ __forceinline__ void tr_tile(const void* src, int stride, int col0, int myrow, float myscale, bf16_t* dst, float* wl, int lane) {
;     ...
;     for (int i = 0; i < 64; ++i) { const int r = rws[i]; float v;
;         if (SRC_BF16) v = bf2f(((const bf16_t*)src)[(size_t)r * stride + col0 + lane]); else v = ((const float*)src)[(size_t)r * stride + col0 + lane] * scs[i];
;         scr[i * 65 + lane] = v; }
	v_lshlrev_b32_e32 v82, 16, v82
	v_lshlrev_b32_e32 v83, 16, v83
	v_lshlrev_b32_e32 v84, 16, v84
	v_lshlrev_b32_e32 v85, 16, v85
	ds_write_b32 v25, v82 offset:4160
	ds_write_b32 v25, v83 offset:4420
	ds_write_b32 v25, v84 offset:4680
	ds_write_b32 v25, v85 offset:4940
	s_waitcnt vmcnt(8)
	v_lshlrev_b32_e32 v86, 16, v86
	v_lshlrev_b32_e32 v87, 16, v87
	v_lshlrev_b32_e32 v88, 16, v88
	v_lshlrev_b32_e32 v89, 16, v89
	ds_write_b32 v25, v86 offset:5200
	ds_write_b32 v25, v87 offset:5460
	ds_write_b32 v25, v88 offset:5720
	ds_write_b32 v25, v89 offset:5980
	s_waitcnt vmcnt(4)
	v_lshlrev_b32_e32 v90, 16, v90
	v_lshlrev_b32_e32 v91, 16, v91
	v_lshlrev_b32_e32 v92, 16, v92
	v_lshlrev_b32_e32 v93, 16, v93
	ds_write_b32 v25, v90 offset:6240
	ds_write_b32 v25, v91 offset:6500
	ds_write_b32 v25, v92 offset:6760
	ds_write_b32 v25, v93 offset:7020
	s_waitcnt vmcnt(0)
	v_lshlrev_b32_e32 v94, 16, v94
	v_lshlrev_b32_e32 v95, 16, v95
	v_lshlrev_b32_e32 v96, 16, v96
	v_lshlrev_b32_e32 v97, 16, v97
	ds_write_b32 v25, v94 offset:7280
	ds_write_b32 v25, v95 offset:7540
	ds_write_b32 v25, v96 offset:7800
	ds_write_b32 v25, v97 offset:8060
	s_waitcnt lgkmcnt(0)
	global_load_ushort v98, v[34:35], off
	global_load_ushort v99, v[30:31], off
	v_mad_i64_i32 v[30:31], s[6:7], v32, s79, v[22:23]
	v_mad_i64_i32 v[32:33], s[6:7], v33, s79, v[22:23]
	global_load_ushort v100, v[30:31], off
	global_load_ushort v101, v[32:33], off
	ds_read_b128 v[30:33], v24 offset:16784
	s_waitcnt lgkmcnt(0)
	v_mad_i64_i32 v[34:35], s[6:7], v30, s79, v[22:23]
	v_mad_i64_i32 v[30:31], s[6:7], v31, s79, v[22:23]
	global_load_ushort v102, v[34:35], off
	global_load_ushort v103, v[30:31], off
	v_mad_i64_i32 v[30:31], s[6:7], v32, s79, v[22:23]
	v_mad_i64_i32 v[32:33], s[6:7], v33, s79, v[22:23]
	global_load_ushort v104, v[30:31], off
	global_load_ushort v105, v[32:33], off
	ds_read_b128 v[30:33], v24 offset:16800
	s_waitcnt lgkmcnt(0)
	v_mad_i64_i32 v[34:35], s[6:7], v30, s79, v[22:23]
	v_mad_i64_i32 v[30:31], s[6:7], v31, s79, v[22:23]
	global_load_ushort v106, v[34:35], off
	global_load_ushort v107, v[30:31], off
	v_mad_i64_i32 v[30:31], s[6:7], v32, s79, v[22:23]
	v_mad_i64_i32 v[32:33], s[6:7], v33, s79, v[22:23]
	global_load_ushort v108, v[30:31], off
	global_load_ushort v109, v[32:33], off
	ds_read_b128 v[30:33], v24 offset:16816
	s_waitcnt lgkmcnt(0)
	v_mad_i64_i32 v[34:35], s[6:7], v30, s79, v[22:23]
	v_mad_i64_i32 v[30:31], s[6:7], v31, s79, v[22:23]
	global_load_ushort v110, v[34:35], off
	global_load_ushort v111, v[30:31], off
	v_mad_i64_i32 v[30:31], s[6:7], v32, s79, v[22:23]
	v_mad_i64_i32 v[32:33], s[6:7], v33, s79, v[22:23]
	global_load_ushort v112, v[30:31], off
	global_load_ushort v113, v[32:33], off
	ds_read_b128 v[30:33], v24 offset:16832
	s_waitcnt lgkmcnt(0)
	v_mad_i64_i32 v[34:35], s[6:7], v30, s79, v[22:23]
	v_mad_i64_i32 v[30:31], s[6:7], v31, s79, v[22:23]
	global_load_ushort v114, v[34:35], off
	global_load_ushort v115, v[30:31], off
	v_mad_i64_i32 v[30:31], s[6:7], v32, s79, v[22:23]
	v_mad_i64_i32 v[32:33], s[6:7], v33, s79, v[22:23]
	global_load_ushort v116, v[30:31], off
	global_load_ushort v117, v[32:33], off
	ds_read_b128 v[30:33], v24 offset:16848
	s_waitcnt lgkmcnt(0)
	v_mad_i64_i32 v[34:35], s[6:7], v30, s79, v[22:23]
	v_mad_i64_i32 v[30:31], s[6:7], v31, s79, v[22:23]
	global_load_ushort v118, v[34:35], off
	global_load_ushort v119, v[30:31], off
	v_mad_i64_i32 v[30:31], s[6:7], v32, s79, v[22:23]
	v_mad_i64_i32 v[32:33], s[6:7], v33, s79, v[22:23]
	global_load_ushort v120, v[30:31], off
	global_load_ushort v121, v[32:33], off
	ds_read_b128 v[30:33], v24 offset:16864
	s_waitcnt lgkmcnt(0)
	v_mad_i64_i32 v[34:35], s[6:7], v30, s79, v[22:23]
	v_mad_i64_i32 v[30:31], s[6:7], v31, s79, v[22:23]
	global_load_ushort v122, v[34:35], off
	global_load_ushort v123, v[30:31], off
	v_mad_i64_i32 v[30:31], s[6:7], v32, s79, v[22:23]
	v_mad_i64_i32 v[32:33], s[6:7], v33, s79, v[22:23]
	global_load_ushort v124, v[30:31], off
	global_load_ushort v125, v[32:33], off
	ds_read_b128 v[30:33], v24 offset:16880
	s_waitcnt lgkmcnt(0)
	v_mad_i64_i32 v[34:35], s[6:7], v30, s79, v[22:23]
	v_mad_i64_i32 v[30:31], s[6:7], v31, s79, v[22:23]
	global_load_ushort v126, v[34:35], off
	global_load_ushort v127, v[30:31], off
	v_mad_i64_i32 v[30:31], s[6:7], v32, s79, v[22:23]
	v_mad_i64_i32 v[22:23], s[6:7], v33, s79, v[22:23]
	global_load_ushort v128, v[30:31], off
	global_load_ushort v129, v[22:23], off
	v_mov_b64_e32 v[22:23], s[90:91]
	v_mad_u64_u32 v[22:23], s[6:7], v0, s66, v[22:23]
	v_add_u32_e32 v0, 0x800, v28
	v_mad_i32_i24 v23, v21, s66, v23
	v_lshl_add_u64 v[18:19], v[18:19], 1, v[22:23]
	s_mov_b32 s6, 0x11000
	s_waitcnt vmcnt(28)
	v_lshlrev_b32_e32 v98, 16, v98
	v_lshlrev_b32_e32 v99, 16, v99
	v_lshlrev_b32_e32 v100, 16, v100
	v_lshlrev_b32_e32 v101, 16, v101
	ds_write_b32 v25, v98 offset:8320
	ds_write_b32 v25, v99 offset:8580
	ds_write_b32 v25, v100 offset:8840
	ds_write_b32 v25, v101 offset:9100
	s_waitcnt vmcnt(24)
	v_lshlrev_b32_e32 v102, 16, v102
	v_lshlrev_b32_e32 v103, 16, v103
	v_lshlrev_b32_e32 v104, 16, v104
	v_lshlrev_b32_e32 v105, 16, v105
	ds_write_b32 v25, v102 offset:9360
	ds_write_b32 v25, v103 offset:9620
	ds_write_b32 v25, v104 offset:9880
	ds_write_b32 v25, v105 offset:10140
	s_waitcnt vmcnt(20)
	v_lshlrev_b32_e32 v106, 16, v106
	v_lshlrev_b32_e32 v107, 16, v107
	v_lshlrev_b32_e32 v108, 16, v108
	v_lshlrev_b32_e32 v109, 16, v109
	ds_write_b32 v25, v106 offset:10400
	ds_write_b32 v25, v107 offset:10660
	ds_write_b32 v25, v108 offset:10920
	ds_write_b32 v25, v109 offset:11180
	s_waitcnt vmcnt(16)
; __device__ __forceinline__ unsigned pk2(float lo, float hi) { return pg8::cvt_pk_bf16(lo, hi); }
; template <bool SRC_BF16> __device__ __forceinline__ void tr_tile(const void* src, int stride, int col0, int myrow, float myscale, bf16_t* dst, float* wl, int lane) {
;     ...
;     asm volatile("s_waitcnt vmcnt(0) lgkmcnt(0)" ::: "memory");
;     const int pb = lane & 7, cl = lane >> 3, ib = 32 * (pb >> 2) + 16 * ((pb >> 1) & 1) + 4 * (pb & 1);
; #pragma unroll
;     for (int k = 0; k < 8; ++k) { const int j = cl + 8 * k; float v[8];
; #pragma unroll
;         for (int jj = 0; jj < 8; ++jj) v[jj] = scr[(ib + 8 * (jj >> 2) + (jj & 3)) * 65 + j];
;         u32x4 w; w.x = pk2(v[0], v[1]); w.y = pk2(v[2], v[3]); w.z = pk2(v[4], v[5]); w.w = pk2(v[6], v[7]);
;         *(u32x4*)(dst + (size_t)j * KVL + 8 * pb) = w; }
	v_lshlrev_b32_e32 v110, 16, v110
	v_lshlrev_b32_e32 v111, 16, v111
	v_lshlrev_b32_e32 v112, 16, v112
	v_lshlrev_b32_e32 v113, 16, v113
	ds_write_b32 v25, v110 offset:11440
	ds_write_b32 v25, v111 offset:11700
	ds_write_b32 v25, v112 offset:11960
	ds_write_b32 v25, v113 offset:12220
	s_waitcnt vmcnt(12)
	v_lshlrev_b32_e32 v114, 16, v114
	v_lshlrev_b32_e32 v115, 16, v115
	v_lshlrev_b32_e32 v116, 16, v116
	v_lshlrev_b32_e32 v117, 16, v117
	ds_write_b32 v25, v114 offset:12480
	ds_write_b32 v25, v115 offset:12740
	ds_write_b32 v25, v116 offset:13000
	ds_write_b32 v25, v117 offset:13260
	s_waitcnt vmcnt(8)
	v_lshlrev_b32_e32 v118, 16, v118
	v_lshlrev_b32_e32 v119, 16, v119
	v_lshlrev_b32_e32 v120, 16, v120
	v_lshlrev_b32_e32 v121, 16, v121
	ds_write_b32 v25, v118 offset:13520
	ds_write_b32 v25, v119 offset:13780
	ds_write_b32 v25, v120 offset:14040
	ds_write_b32 v25, v121 offset:14300
	s_waitcnt vmcnt(4)
	v_lshlrev_b32_e32 v122, 16, v122
	v_lshlrev_b32_e32 v123, 16, v123
	v_lshlrev_b32_e32 v124, 16, v124
	v_lshlrev_b32_e32 v125, 16, v125
	ds_write_b32 v25, v122 offset:14560
	ds_write_b32 v25, v123 offset:14820
	ds_write_b32 v25, v124 offset:15080
	ds_write_b32 v25, v125 offset:15340
	s_waitcnt vmcnt(0)
	v_lshlrev_b32_e32 v126, 16, v126
	v_lshlrev_b32_e32 v127, 16, v127
	v_lshlrev_b32_e32 v128, 16, v128
	v_lshlrev_b32_e32 v129, 16, v129
	ds_write_b32 v25, v126 offset:15600
	ds_write_b32 v25, v127 offset:15860
	ds_write_b32 v25, v128 offset:16120
	ds_write_b32 v25, v129 offset:16380
	s_waitcnt vmcnt(0) lgkmcnt(0)
	ds_read2_b32 v[30:31], v28 offset0:65 offset1:73
	ds_read2_b32 v[32:33], v28 offset1:8
	ds_read2_b32 v[34:35], v28 offset0:130 offset1:138
	ds_read2_b32 v[36:37], v28 offset0:195 offset1:203
	ds_read2_b32 v[38:39], v0 offset0:8 offset1:16
	ds_read2_b32 v[40:41], v0 offset0:73 offset1:81
	ds_read2_b32 v[42:43], v0 offset0:138 offset1:146
	ds_read2_b32 v[44:45], v0 offset0:203 offset1:211
	v_mov_b32_e32 v7, v1
	v_lshl_add_u64 v[22:23], v[18:19], 0, v[6:7]
	v_mov_b32_e32 v9, v1
	v_lshl_add_u64 v[46:47], v[22:23], 0, v[8:9]
	s_waitcnt lgkmcnt(6)
	v_cvt_pk_bf16_f32 v18, v32, v30
	s_waitcnt lgkmcnt(4)
	v_cvt_pk_bf16_f32 v19, v34, v36
	s_waitcnt lgkmcnt(2)
	v_cvt_pk_bf16_f32 v20, v38, v40
	s_waitcnt lgkmcnt(0)
	v_cvt_pk_bf16_f32 v21, v42, v44
	v_add_co_u32_e32 v30, vcc, s6, v46
	global_store_dwordx4 v[46:47], v[18:21], off
	s_movk_i32 s6, 0x87f
	s_nop 0
	v_cvt_pk_bf16_f32 v18, v33, v31
	v_cvt_pk_bf16_f32 v19, v35, v37
	v_cvt_pk_bf16_f32 v20, v39, v41
	v_cvt_pk_bf16_f32 v21, v43, v45
	v_addc_co_u32_e32 v31, vcc, 0, v47, vcc
	global_store_dwordx4 v[30:31], v[18:21], off
	ds_read2_b32 v[30:31], v28 offset0:81 offset1:89
	ds_read2_b32 v[32:33], v28 offset0:16 offset1:24
	ds_read2_b32 v[34:35], v28 offset0:146 offset1:154
	ds_read2_b32 v[36:37], v28 offset0:211 offset1:219
	ds_read2_b32 v[38:39], v0 offset0:24 offset1:32
	ds_read2_b32 v[40:41], v0 offset0:89 offset1:97
	ds_read2_b32 v[42:43], v0 offset0:154 offset1:162
	ds_read2_b32 v[44:45], v0 offset0:219 offset1:227
	v_add_co_u32_e32 v48, vcc, s76, v46
	s_waitcnt lgkmcnt(6)
	v_cvt_pk_bf16_f32 v18, v32, v30
	v_addc_co_u32_e32 v49, vcc, 0, v47, vcc
	s_waitcnt lgkmcnt(4)
	v_cvt_pk_bf16_f32 v19, v34, v36
	s_waitcnt lgkmcnt(2)
	v_cvt_pk_bf16_f32 v20, v38, v40
	s_waitcnt lgkmcnt(0)
	v_cvt_pk_bf16_f32 v21, v42, v44
	v_add_co_u32_e32 v30, vcc, s17, v46
	global_store_dwordx4 v[48:49], v[18:21], off
	s_nop 1
	v_cvt_pk_bf16_f32 v18, v33, v31
	v_cvt_pk_bf16_f32 v19, v35, v37
	v_cvt_pk_bf16_f32 v20, v39, v41
	v_cvt_pk_bf16_f32 v21, v43, v45
	v_addc_co_u32_e32 v31, vcc, 0, v47, vcc
	global_store_dwordx4 v[30:31], v[18:21], off
	ds_read2_b32 v[30:31], v28 offset0:97 offset1:105
	ds_read2_b32 v[32:33], v28 offset0:32 offset1:40
	ds_read2_b32 v[34:35], v28 offset0:162 offset1:170
	ds_read2_b32 v[36:37], v28 offset0:227 offset1:235
	ds_read2_b32 v[38:39], v0 offset0:40 offset1:48
	ds_read2_b32 v[40:41], v0 offset0:105 offset1:113
	ds_read2_b32 v[42:43], v0 offset0:170 offset1:178
	ds_read2_b32 v[44:45], v0 offset0:235 offset1:243
	s_waitcnt lgkmcnt(6)
	v_cvt_pk_bf16_f32 v18, v32, v30
	s_waitcnt lgkmcnt(4)
	v_cvt_pk_bf16_f32 v19, v34, v36
	s_waitcnt lgkmcnt(2)
	v_cvt_pk_bf16_f32 v20, v38, v40
	v_lshl_add_u64 v[46:47], v[22:23], 0, v[10:11]
	s_waitcnt lgkmcnt(0)
	v_cvt_pk_bf16_f32 v21, v42, v44
	global_store_dwordx4 v[46:47], v[18:21], off
	v_lshl_add_u64 v[46:47], v[22:23], 0, v[14:15]
	v_cmp_lt_i32_e32 vcc, s6, v3
	v_cvt_pk_bf16_f32 v18, v33, v31
	v_cvt_pk_bf16_f32 v19, v35, v37
	v_cvt_pk_bf16_f32 v20, v39, v41
	v_cvt_pk_bf16_f32 v21, v43, v45
	v_lshl_add_u64 v[30:31], v[22:23], 0, v[12:13]
	global_store_dwordx4 v[30:31], v[18:21], off
	ds_read2_b32 v[30:31], v28 offset0:48 offset1:56
	ds_read2_b32 v[32:33], v28 offset0:113 offset1:121
	ds_read2_b32 v[34:35], v28 offset0:178 offset1:186
	ds_read2_b32 v[36:37], v28 offset0:243 offset1:251
	ds_read2_b32 v[38:39], v0 offset0:56 offset1:64
	ds_read2_b32 v[40:41], v0 offset0:121 offset1:129
	ds_read2_b32 v[42:43], v0 offset0:186 offset1:194
	v_add_u32_e32 v0, 0xa00, v28
	ds_read2_b32 v[44:45], v0 offset0:123 offset1:131
	s_waitcnt lgkmcnt(6)
	v_cvt_pk_bf16_f32 v18, v30, v32
	s_waitcnt lgkmcnt(4)
	v_cvt_pk_bf16_f32 v19, v34, v36
	s_waitcnt lgkmcnt(2)
	v_cvt_pk_bf16_f32 v20, v38, v40
	v_lshl_add_u64 v[22:23], v[22:23], 0, v[16:17]
	s_waitcnt lgkmcnt(0)
	v_cvt_pk_bf16_f32 v21, v42, v44
	global_store_dwordx4 v[46:47], v[18:21], off
	s_or_b64 s[4:5], vcc, s[4:5]
	s_nop 0
	v_cvt_pk_bf16_f32 v18, v31, v33
	v_cvt_pk_bf16_f32 v19, v35, v37
	v_cvt_pk_bf16_f32 v20, v39, v41
	v_cvt_pk_bf16_f32 v21, v43, v45
	global_store_dwordx4 v[22:23], v[18:21], off
	s_waitcnt lgkmcnt(0)
	s_andn2_b64 exec, exec, s[4:5]
	s_cbranch_execz .LBB0_240

; __device__ __forceinline__ float siluf_(float x) { return x / (1.f + __expf(-x)); }
; __device__ __forceinline__ void prep_phase(const Args& a, int l, float* lds) {
;     ...
;     for (int idx = gt; idx < MROWS * 192; idx += GT) {
;         const int k8 = idx % 192, row = idx / 192, ch0 = 8 * k8;
;         const bool lat = row < MLAT; const int t = lat ? (row & 4095) : ((row - MLAT) & 255); const int n = lat ? SEQ : CTXL;
;         float acc[8];
;         { const f32x4 b0 = *(const f32x4*)(cb + ch0), b1 = *(const f32x4*)(cb + ch0 + 4);
; #pragma unroll
;           for (int j = 0; j < 4; ++j) { acc[j] = b0[j]; acc[4 + j] = b1[j]; } }
; #pragma unroll
;         for (int j = 0; j < 5; ++j) { const int tt = t + j - 2;
;             if (tt >= 0 && tt < n) { const u32x4 xw = *(const u32x4*)(P + (size_t)(row + j - 2) * NINP + XBCOFF + ch0); float x[8]; unpack8(xw, x);
;                 const f32x4 w0 = *(const f32x4*)(cw + j * 1536 + ch0), w1 = *(const f32x4*)(cw + j * 1536 + ch0 + 4);
; #pragma unroll
;                 for (int q = 0; q < 4; ++q) { acc[q] += w0[q] * x[q]; acc[4 + q] += w1[q] * x[4 + q]; } } }
;         f32x4 o0, o1;
; #pragma unroll
;         for (int q = 0; q < 4; ++q) { o0[q] = siluf_(acc[q]); o1[q] = siluf_(acc[4 + q]); }
;         *(f32x4*)(xbc + (size_t)row * 1536 + ch0) = o0; *(f32x4*)(xbc + (size_t)row * 1536 + ch0 + 4) = o1;
.LBB0_243:
	v_mul_hi_i32 v2, v14, s20
	v_lshrrev_b32_e32 v3, 31, v2
	v_ashrrev_i32_e32 v2, 5, v2
	v_add_u32_e32 v15, v2, v3
	s_movk_i32 s0, 0xfa00
	v_mad_u64_u32 v[10:11], s[0:1], v15, s0, v[0:1]
	v_ashrrev_i32_e32 v11, 31, v10
	v_lshlrev_b64 v[12:13], 2, v[10:11]
	v_lshl_add_u64 v[6:7], s[8:9], 0, v[12:13]
	global_load_dwordx4 v[2:5], v[6:7], off offset:16
	s_nop 0
	global_load_dwordx4 v[6:9], v[6:7], off
	s_mov_b32 s0, 0x180000
	v_cmp_gt_i32_e32 vcc, s0, v14
	v_mov_b32_e32 v16, 0xfff
	v_bfrev_b32_e32 v17, 4.0
	v_cndmask_b32_e32 v16, v204, v16, vcc
	v_mov_b32_e32 v18, 0x1002
	v_and_b32_e32 v16, v16, v15
	v_cndmask_b32_e32 v17, v17, v18, vcc
	v_lshl_add_u64 v[12:13], s[6:7], 0, v[12:13]
	v_mov_b64_e32 v[110:111], s[96:97]
	v_mad_i64_i32 v[110:111], s[16:17], v15, s79, v[110:111]
	v_lshl_add_u64 v[110:111], v[10:11], 1, v[110:111]
	v_add_co_u32_e32 v110, vcc, 0x2000, v110
	s_nop 1
	v_addc_co_u32_e32 v111, vcc, 0, v111, vcc
	s_mov_b32 s16, 0xffff3400
	s_mov_b32 s17, -1
	v_lshl_add_u64 v[112:113], v[110:111], 0, s[16:17]
	global_load_dwordx4 v[50:53], v[112:113], off
	global_load_dwordx4 v[70:73], v[12:13], off
	global_load_dwordx4 v[74:77], v[12:13], off offset:16
	s_mov_b32 s16, 0xffff9a00
	s_mov_b32 s17, -1
	v_lshl_add_u64 v[112:113], v[110:111], 0, s[16:17]
	global_load_dwordx4 v[54:57], v[112:113], off
	s_mov_b64 s[16:17], 0x1800
	v_lshl_add_u64 v[114:115], v[12:13], 0, s[16:17]
	global_load_dwordx4 v[78:81], v[114:115], off
	global_load_dwordx4 v[82:85], v[114:115], off offset:16
	global_load_dwordx4 v[58:61], v[110:111], off
	s_mov_b64 s[16:17], 0x3000
	v_lshl_add_u64 v[114:115], v[12:13], 0, s[16:17]
	global_load_dwordx4 v[86:89], v[114:115], off
	global_load_dwordx4 v[90:93], v[114:115], off offset:16
	s_mov_b32 s16, 0x6600
	s_mov_b32 s17, 0
	v_lshl_add_u64 v[112:113], v[110:111], 0, s[16:17]
	global_load_dwordx4 v[62:65], v[112:113], off
	s_mov_b64 s[16:17], 0x4800
	v_lshl_add_u64 v[114:115], v[12:13], 0, s[16:17]
	global_load_dwordx4 v[94:97], v[114:115], off
	global_load_dwordx4 v[98:101], v[114:115], off offset:16
	s_mov_b32 s16, 0xcc00
	s_mov_b32 s17, 0
	v_lshl_add_u64 v[112:113], v[110:111], 0, s[16:17]
	global_load_dwordx4 v[66:69], v[112:113], off
	s_mov_b64 s[16:17], 0x6000
	v_lshl_add_u64 v[114:115], v[12:13], 0, s[16:17]
	global_load_dwordx4 v[102:105], v[114:115], off
	global_load_dwordx4 v[106:109], v[114:115], off offset:16
	s_waitcnt vmcnt(12)
	v_cmp_lt_u32_e32 vcc, 1, v16
	v_cmp_lt_u32_e64 s[0:1], v16, v17
	s_and_b64 s[16:17], vcc, s[0:1]
	s_and_saveexec_b64 s[0:1], s[16:17]
	v_lshlrev_b32_e32 v116, 16, v50
	v_and_b32_e32 v117, 0xffff0000, v50
	v_lshlrev_b32_e32 v118, 16, v51
	v_and_b32_e32 v119, 0xffff0000, v51
	v_pk_fma_f32 v[6:7], v[70:71], v[116:117], v[6:7]
	v_lshlrev_b32_e32 v120, 16, v52
	v_and_b32_e32 v121, 0xffff0000, v52
	v_pk_fma_f32 v[8:9], v[72:73], v[118:119], v[8:9]
	v_lshlrev_b32_e32 v122, 16, v53
	v_and_b32_e32 v123, 0xffff0000, v53
	v_pk_fma_f32 v[2:3], v[74:75], v[120:121], v[2:3]
	v_pk_fma_f32 v[4:5], v[76:77], v[122:123], v[4:5]
	s_or_b64 exec, exec, s[0:1]
	s_waitcnt vmcnt(9)
	v_add_u32_e32 v124, 1, v16
	v_cmp_ne_u32_e32 vcc, 0, v16
	v_cmp_lt_u32_e64 s[0:1], v124, v17
	s_and_b64 s[16:17], vcc, s[0:1]
	s_and_saveexec_b64 s[0:1], s[16:17]
	v_lshlrev_b32_e32 v116, 16, v54
	v_and_b32_e32 v117, 0xffff0000, v54
	v_lshlrev_b32_e32 v118, 16, v55
	v_and_b32_e32 v119, 0xffff0000, v55
	v_pk_fma_f32 v[6:7], v[78:79], v[116:117], v[6:7]
	v_lshlrev_b32_e32 v120, 16, v56
	v_and_b32_e32 v121, 0xffff0000, v56
	v_pk_fma_f32 v[8:9], v[80:81], v[118:119], v[8:9]
	v_lshlrev_b32_e32 v122, 16, v57
	v_and_b32_e32 v123, 0xffff0000, v57
	v_pk_fma_f32 v[2:3], v[82:83], v[120:121], v[2:3]
	v_pk_fma_f32 v[4:5], v[84:85], v[122:123], v[4:5]
	s_or_b64 exec, exec, s[0:1]
	s_waitcnt vmcnt(6)
	v_add_u32_e32 v124, 2, v16
	v_cmp_lt_u32_e32 vcc, v124, v17
	s_and_saveexec_b64 s[0:1], vcc
	v_lshlrev_b32_e32 v116, 16, v58
	v_and_b32_e32 v117, 0xffff0000, v58
	v_lshlrev_b32_e32 v118, 16, v59
	v_and_b32_e32 v119, 0xffff0000, v59
	v_pk_fma_f32 v[6:7], v[86:87], v[116:117], v[6:7]
	v_lshlrev_b32_e32 v120, 16, v60
	v_and_b32_e32 v121, 0xffff0000, v60
	v_pk_fma_f32 v[8:9], v[88:89], v[118:119], v[8:9]
	v_lshlrev_b32_e32 v122, 16, v61
	v_and_b32_e32 v123, 0xffff0000, v61
	v_pk_fma_f32 v[2:3], v[90:91], v[120:121], v[2:3]
	v_pk_fma_f32 v[4:5], v[92:93], v[122:123], v[4:5]
	s_or_b64 exec, exec, s[0:1]
	s_waitcnt vmcnt(3)
	v_add_u32_e32 v124, 3, v16
	v_cmp_lt_u32_e32 vcc, v124, v17
	s_and_saveexec_b64 s[0:1], vcc
	v_lshlrev_b32_e32 v116, 16, v62
	v_and_b32_e32 v117, 0xffff0000, v62
	v_lshlrev_b32_e32 v118, 16, v63
	v_and_b32_e32 v119, 0xffff0000, v63
	v_pk_fma_f32 v[6:7], v[94:95], v[116:117], v[6:7]
	v_lshlrev_b32_e32 v120, 16, v64
	v_and_b32_e32 v121, 0xffff0000, v64
	v_pk_fma_f32 v[8:9], v[96:97], v[118:119], v[8:9]
	v_lshlrev_b32_e32 v122, 16, v65
	v_and_b32_e32 v123, 0xffff0000, v65
	v_pk_fma_f32 v[2:3], v[98:99], v[120:121], v[2:3]
	v_pk_fma_f32 v[4:5], v[100:101], v[122:123], v[4:5]
	s_or_b64 exec, exec, s[0:1]
	s_waitcnt vmcnt(0)
	v_add_u32_e32 v124, 4, v16
	v_cmp_lt_u32_e32 vcc, v124, v17
	s_and_saveexec_b64 s[0:1], vcc
	v_lshlrev_b32_e32 v116, 16, v66
	v_and_b32_e32 v117, 0xffff0000, v66
	v_lshlrev_b32_e32 v118, 16, v67
	v_and_b32_e32 v119, 0xffff0000, v67
	v_pk_fma_f32 v[6:7], v[102:103], v[116:117], v[6:7]
	v_lshlrev_b32_e32 v120, 16, v68
	v_and_b32_e32 v121, 0xffff0000, v68
	v_pk_fma_f32 v[8:9], v[104:105], v[118:119], v[8:9]
	v_lshlrev_b32_e32 v122, 16, v69
	v_and_b32_e32 v123, 0xffff0000, v69
	v_pk_fma_f32 v[2:3], v[106:107], v[120:121], v[2:3]
	v_pk_fma_f32 v[4:5], v[108:109], v[122:123], v[4:5]
	s_or_b64 exec, exec, s[0:1]
	s_branch .LBB0_242

; __device__ __forceinline__ float bf2f(unsigned v) { return __uint_as_float(v << 16); }
; template <bool SRC_BF16> __device__ __forceinline__ void tr_tile(const void* src, int stride, int col0, int myrow, float myscale, bf16_t* dst, float* wl, int lane) {
;     float* scr = wl; int* rws = (int*)(wl + 64 * 65); float* scs = wl + 64 * 65 + 64;
;     rws[lane] = myrow; scs[lane] = myscale;
;     asm volatile("s_waitcnt lgkmcnt(0)" ::: "memory");
; #pragma unroll 32
;     for (int i = 0; i < 64; ++i) { const int r = rws[i]; float v;
;         if (SRC_BF16) v = bf2f(((const bf16_t*)src)[(size_t)r * stride + col0 + lane]); else v = ((const float*)src)[(size_t)r * stride + col0 + lane] * scs[i];
;         scr[i * 65 + lane] = v; }
; __device__ __forceinline__ void prep2_phase(const Args& a, float* lds) {
;     ...
;           if (tI < 4 * 16 * 68) { const int pt = tI % 68, rest = tI / 68, head = rest & 15, bd = rest >> 4, b = bd >> 1, dir = bd & 1;
;               const int row = seq_row(b, dir, 64 * pt + lane);
;               tr_tile<false>(xbc, 1536, head * 64, row, dtv[row * 64 + dir * 16 + head], XDT + ((size_t)bd * 1024 + head * 64) * KVL + 64 * pt, wl, lane);
.LBB0_313:
	s_or_b64 exec, exec, s[0:1]
	v_and_b32_e32 v19, 15, v3
	v_lshlrev_b32_e32 v3, 6, v5
	v_lshlrev_b32_e32 v0, 4, v0
	v_or3_b32 v28, v3, v0, v19
	v_ashrrev_i32_e32 v29, 31, v28
	v_lshl_add_u64 v[28:29], v[28:29], 2, s[22:23]
	global_load_dword v0, v[28:29], off
	v_ashrrev_i32_e32 v3, 31, v2
	v_add_u32_e32 v26, v17, v4
	v_lshlrev_b64 v[28:29], 10, v[2:3]
	v_ashrrev_i32_e32 v27, 31, v26
	s_waitcnt vmcnt(0)
	ds_write2st64_b32 v13, v5, v0 offset0:65 offset1:66
	s_waitcnt lgkmcnt(0)
	ds_read_b128 v[2:5], v11 offset:16640
	ds_read_b128 v[32:35], v11 offset:16656
	v_lshlrev_b32_e32 v0, 8, v19
	v_lshl_add_u64 v[30:31], v[20:21], 0, v[0:1]
	v_lshl_or_b32 v0, v19, 6, v28
	s_waitcnt lgkmcnt(0)
	v_mad_i64_i32 v[36:37], s[0:1], v2, s78, v[30:31]
	v_mad_i64_i32 v[2:3], s[0:1], v3, s78, v[30:31]
	global_load_dword v66, v[36:37], off
	global_load_dword v67, v[2:3], off
	s_waitcnt lgkmcnt(0)
	v_mad_i64_i32 v[2:3], s[0:1], v4, s78, v[30:31]
	v_mad_i64_i32 v[4:5], s[0:1], v5, s78, v[30:31]
	global_load_dword v68, v[2:3], off
	s_nop 0
	global_load_dword v69, v[4:5], off
	v_mad_i64_i32 v[4:5], s[0:1], v33, s78, v[30:31]
	v_mad_i64_i32 v[2:3], s[0:1], v32, s78, v[30:31]
	global_load_dword v70, v[2:3], off
	global_load_dword v71, v[4:5], off
	s_waitcnt lgkmcnt(0)
	v_mad_i64_i32 v[2:3], s[0:1], v34, s78, v[30:31]
	v_mad_i64_i32 v[32:33], s[0:1], v35, s78, v[30:31]
	global_load_dword v72, v[2:3], off
	s_nop 0
	global_load_dword v73, v[32:33], off
	ds_read_b128 v[2:5], v11 offset:16672
	ds_read_b128 v[32:35], v11 offset:16688
	s_waitcnt lgkmcnt(0)
	v_mad_i64_i32 v[36:37], s[0:1], v2, s78, v[30:31]
	v_mad_i64_i32 v[2:3], s[0:1], v3, s78, v[30:31]
	global_load_dword v74, v[36:37], off
	global_load_dword v75, v[2:3], off
	s_waitcnt lgkmcnt(0)
	v_mad_i64_i32 v[2:3], s[0:1], v4, s78, v[30:31]
	v_mad_i64_i32 v[4:5], s[0:1], v5, s78, v[30:31]
	global_load_dword v76, v[2:3], off
	s_nop 0
	global_load_dword v77, v[4:5], off
	v_mad_i64_i32 v[4:5], s[0:1], v33, s78, v[30:31]
	v_mad_i64_i32 v[2:3], s[0:1], v32, s78, v[30:31]
	global_load_dword v78, v[2:3], off
	global_load_dword v79, v[4:5], off
	s_waitcnt lgkmcnt(0)
	v_mad_i64_i32 v[2:3], s[0:1], v34, s78, v[30:31]
	v_mad_i64_i32 v[32:33], s[0:1], v35, s78, v[30:31]
	global_load_dword v80, v[2:3], off
	s_nop 0
	global_load_dword v81, v[32:33], off
	ds_read_b128 v[2:5], v11 offset:16704
	ds_read_b128 v[32:35], v11 offset:16720
	s_waitcnt lgkmcnt(0)
	v_mad_i64_i32 v[36:37], s[0:1], v2, s78, v[30:31]
	v_mad_i64_i32 v[2:3], s[0:1], v3, s78, v[30:31]
	global_load_dword v82, v[36:37], off
	global_load_dword v83, v[2:3], off
	s_waitcnt lgkmcnt(0)
	v_mad_i64_i32 v[2:3], s[0:1], v4, s78, v[30:31]
	v_mad_i64_i32 v[4:5], s[0:1], v5, s78, v[30:31]
	global_load_dword v84, v[2:3], off
	s_nop 0
	global_load_dword v85, v[4:5], off
	v_mad_i64_i32 v[4:5], s[0:1], v33, s78, v[30:31]
	v_mad_i64_i32 v[2:3], s[0:1], v32, s78, v[30:31]
	global_load_dword v86, v[2:3], off
	global_load_dword v87, v[4:5], off
	s_waitcnt lgkmcnt(0)
	v_mad_i64_i32 v[2:3], s[0:1], v34, s78, v[30:31]
	v_mad_i64_i32 v[32:33], s[0:1], v35, s78, v[30:31]
	global_load_dword v88, v[2:3], off
	s_nop 0
	global_load_dword v89, v[32:33], off
	ds_read_b128 v[2:5], v11 offset:16736
	s_waitcnt lgkmcnt(0)
	v_mad_i64_i32 v[32:33], s[0:1], v2, s78, v[30:31]
	v_mad_i64_i32 v[2:3], s[0:1], v3, s78, v[30:31]
	global_load_dword v90, v[32:33], off
	global_load_dword v91, v[2:3], off
	s_waitcnt lgkmcnt(0)
	v_mad_i64_i32 v[2:3], s[0:1], v4, s78, v[30:31]
	v_mad_i64_i32 v[4:5], s[0:1], v5, s78, v[30:31]
	global_load_dword v92, v[2:3], off
	s_nop 0
	global_load_dword v93, v[4:5], off
	ds_read_b128 v[2:5], v11 offset:16752
	s_waitcnt lgkmcnt(0)
	v_mad_i64_i32 v[32:33], s[0:1], v2, s78, v[30:31]
	v_mad_i64_i32 v[2:3], s[0:1], v3, s78, v[30:31]
	global_load_dword v94, v[32:33], off
	global_load_dword v95, v[2:3], off
	s_waitcnt lgkmcnt(0)
	v_mad_i64_i32 v[2:3], s[0:1], v4, s78, v[30:31]
	v_mad_i64_i32 v[4:5], s[0:1], v5, s78, v[30:31]
	global_load_dword v96, v[2:3], off
	s_nop 0
	global_load_dword v97, v[4:5], off
	ds_read_b128 v[2:5], v11 offset:16768
	s_waitcnt lgkmcnt(0)
	v_mad_i64_i32 v[32:33], s[0:1], v2, s78, v[30:31]
	v_mad_i64_i32 v[2:3], s[0:1], v3, s78, v[30:31]
	ds_read_b128 v[130:133], v11 offset:16896
	ds_read_b128 v[134:137], v11 offset:16912
	s_waitcnt vmcnt(28) lgkmcnt(1)
	v_pk_mul_f32 v[66:67], v[66:67], v[130:131]
	v_pk_mul_f32 v[68:69], v[68:69], v[132:133]
	ds_write_b32 v13, v66 offset:0
	ds_write_b32 v13, v67 offset:260
	ds_write_b32 v13, v68 offset:520
	ds_write_b32 v13, v69 offset:780
	ds_read_b128 v[130:133], v11 offset:16928
	s_waitcnt vmcnt(24) lgkmcnt(1)
	v_pk_mul_f32 v[70:71], v[70:71], v[134:135]
	v_pk_mul_f32 v[72:73], v[72:73], v[136:137]
	ds_write_b32 v13, v70 offset:1040
	ds_write_b32 v13, v71 offset:1300
	ds_write_b32 v13, v72 offset:1560
	ds_write_b32 v13, v73 offset:1820
	ds_read_b128 v[134:137], v11 offset:16944
	s_waitcnt vmcnt(20) lgkmcnt(1)
	v_pk_mul_f32 v[74:75], v[74:75], v[130:131]
	v_pk_mul_f32 v[76:77], v[76:77], v[132:133]
	ds_write_b32 v13, v74 offset:2080
	ds_write_b32 v13, v75 offset:2340
	ds_write_b32 v13, v76 offset:2600
	ds_write_b32 v13, v77 offset:2860
	ds_read_b128 v[130:133], v11 offset:16960
	s_waitcnt vmcnt(16) lgkmcnt(1)
	v_pk_mul_f32 v[78:79], v[78:79], v[134:135]
	v_pk_mul_f32 v[80:81], v[80:81], v[136:137]
	ds_write_b32 v13, v78 offset:3120
	ds_write_b32 v13, v79 offset:3380
	ds_write_b32 v13, v80 offset:3640
	ds_write_b32 v13, v81 offset:3900
	ds_read_b128 v[134:137], v11 offset:16976
	s_waitcnt vmcnt(12) lgkmcnt(1)
; __device__ __forceinline__ float bf2f(unsigned v) { return __uint_as_float(v << 16); }
; template <bool SRC_BF16> __device__ __forceinline__ void tr_tile(const void* src, int stride, int col0, int myrow, float myscale, bf16_t* dst, float* wl, int lane) {
;     ...
;     for (int i = 0; i < 64; ++i) { const int r = rws[i]; float v;
;         if (SRC_BF16) v = bf2f(((const bf16_t*)src)[(size_t)r * stride + col0 + lane]); else v = ((const float*)src)[(size_t)r * stride + col0 + lane] * scs[i];
;         scr[i * 65 + lane] = v; }
	v_pk_mul_f32 v[82:83], v[82:83], v[130:131]
	v_pk_mul_f32 v[84:85], v[84:85], v[132:133]
	ds_write_b32 v13, v82 offset:4160
	ds_write_b32 v13, v83 offset:4420
	ds_write_b32 v13, v84 offset:4680
	ds_write_b32 v13, v85 offset:4940
	ds_read_b128 v[130:133], v11 offset:16992
	s_waitcnt vmcnt(8) lgkmcnt(1)
	v_pk_mul_f32 v[86:87], v[86:87], v[134:135]
	v_pk_mul_f32 v[88:89], v[88:89], v[136:137]
	ds_write_b32 v13, v86 offset:5200
	ds_write_b32 v13, v87 offset:5460
	ds_write_b32 v13, v88 offset:5720
	ds_write_b32 v13, v89 offset:5980
	ds_read_b128 v[134:137], v11 offset:17008
	s_waitcnt vmcnt(4) lgkmcnt(1)
	v_pk_mul_f32 v[90:91], v[90:91], v[130:131]
	v_pk_mul_f32 v[92:93], v[92:93], v[132:133]
	ds_write_b32 v13, v90 offset:6240
	ds_write_b32 v13, v91 offset:6500
	ds_write_b32 v13, v92 offset:6760
	ds_write_b32 v13, v93 offset:7020
	s_waitcnt vmcnt(0) lgkmcnt(0)
	v_pk_mul_f32 v[94:95], v[94:95], v[134:135]
	v_pk_mul_f32 v[96:97], v[96:97], v[136:137]
	ds_write_b32 v13, v94 offset:7280
	ds_write_b32 v13, v95 offset:7540
	ds_write_b32 v13, v96 offset:7800
	ds_write_b32 v13, v97 offset:8060
	s_waitcnt lgkmcnt(0)
	global_load_dword v98, v[32:33], off
	global_load_dword v99, v[2:3], off
	s_waitcnt lgkmcnt(0)
	v_mad_i64_i32 v[2:3], s[0:1], v4, s78, v[30:31]
	v_mad_i64_i32 v[4:5], s[0:1], v5, s78, v[30:31]
	global_load_dword v100, v[2:3], off
	s_nop 0
	global_load_dword v101, v[4:5], off
	ds_read_b128 v[2:5], v11 offset:16784
	s_waitcnt lgkmcnt(0)
	v_mad_i64_i32 v[32:33], s[0:1], v2, s78, v[30:31]
	v_mad_i64_i32 v[2:3], s[0:1], v3, s78, v[30:31]
	global_load_dword v102, v[32:33], off
	global_load_dword v103, v[2:3], off
	s_waitcnt lgkmcnt(0)
	v_mad_i64_i32 v[2:3], s[0:1], v4, s78, v[30:31]
	v_mad_i64_i32 v[4:5], s[0:1], v5, s78, v[30:31]
	global_load_dword v104, v[2:3], off
	s_nop 0
	global_load_dword v105, v[4:5], off
	ds_read_b128 v[2:5], v11 offset:16800
	s_waitcnt lgkmcnt(0)
	v_mad_i64_i32 v[32:33], s[0:1], v2, s78, v[30:31]
	v_mad_i64_i32 v[2:3], s[0:1], v3, s78, v[30:31]
	global_load_dword v106, v[32:33], off
	global_load_dword v107, v[2:3], off
	s_waitcnt lgkmcnt(0)
	v_mad_i64_i32 v[2:3], s[0:1], v4, s78, v[30:31]
	v_mad_i64_i32 v[4:5], s[0:1], v5, s78, v[30:31]
	global_load_dword v108, v[2:3], off
	s_nop 0
	global_load_dword v109, v[4:5], off
	ds_read_b128 v[2:5], v11 offset:16816
	s_waitcnt lgkmcnt(0)
	v_mad_i64_i32 v[32:33], s[0:1], v2, s78, v[30:31]
	v_mad_i64_i32 v[2:3], s[0:1], v3, s78, v[30:31]
	global_load_dword v110, v[32:33], off
	global_load_dword v111, v[2:3], off
	s_waitcnt lgkmcnt(0)
	v_mad_i64_i32 v[2:3], s[0:1], v4, s78, v[30:31]
	v_mad_i64_i32 v[4:5], s[0:1], v5, s78, v[30:31]
	global_load_dword v112, v[2:3], off
	s_nop 0
	global_load_dword v113, v[4:5], off
	ds_read_b128 v[2:5], v11 offset:16832
	s_waitcnt lgkmcnt(0)
	v_mad_i64_i32 v[32:33], s[0:1], v2, s78, v[30:31]
	v_mad_i64_i32 v[2:3], s[0:1], v3, s78, v[30:31]
	global_load_dword v114, v[32:33], off
	global_load_dword v115, v[2:3], off
	s_waitcnt lgkmcnt(0)
	v_mad_i64_i32 v[2:3], s[0:1], v4, s78, v[30:31]
	v_mad_i64_i32 v[4:5], s[0:1], v5, s78, v[30:31]
	global_load_dword v116, v[2:3], off
	s_nop 0
	global_load_dword v117, v[4:5], off
	ds_read_b128 v[2:5], v11 offset:16848
	s_waitcnt lgkmcnt(0)
	v_mad_i64_i32 v[32:33], s[0:1], v2, s78, v[30:31]
	v_mad_i64_i32 v[2:3], s[0:1], v3, s78, v[30:31]
	global_load_dword v118, v[32:33], off
	global_load_dword v119, v[2:3], off
	s_waitcnt lgkmcnt(0)
	v_mad_i64_i32 v[2:3], s[0:1], v4, s78, v[30:31]
	v_mad_i64_i32 v[4:5], s[0:1], v5, s78, v[30:31]
	global_load_dword v120, v[2:3], off
	s_nop 0
	global_load_dword v121, v[4:5], off
	ds_read_b128 v[2:5], v11 offset:16864
	s_waitcnt lgkmcnt(0)
	v_mad_i64_i32 v[32:33], s[0:1], v2, s78, v[30:31]
	v_mad_i64_i32 v[2:3], s[0:1], v3, s78, v[30:31]
	global_load_dword v122, v[32:33], off
	global_load_dword v123, v[2:3], off
	s_waitcnt lgkmcnt(0)
	v_mad_i64_i32 v[2:3], s[0:1], v4, s78, v[30:31]
	v_mad_i64_i32 v[4:5], s[0:1], v5, s78, v[30:31]
	global_load_dword v124, v[2:3], off
	s_nop 0
	global_load_dword v125, v[4:5], off
	ds_read_b128 v[32:35], v11 offset:16880
	s_waitcnt lgkmcnt(0)
	v_mad_i64_i32 v[2:3], s[0:1], v32, s78, v[30:31]
	v_mad_i64_i32 v[4:5], s[0:1], v33, s78, v[30:31]
	global_load_dword v126, v[2:3], off
	global_load_dword v127, v[4:5], off
	s_waitcnt lgkmcnt(0)
	v_mad_i64_i32 v[2:3], s[0:1], v34, s78, v[30:31]
	v_mad_i64_i32 v[30:31], s[0:1], v35, s78, v[30:31]
	global_load_dword v128, v[2:3], off
	s_nop 0
	global_load_dword v129, v[30:31], off
	v_mov_b64_e32 v[2:3], s[36:37]
	v_mad_u64_u32 v[2:3], s[0:1], v0, s66, v[2:3]
	ds_read_b128 v[130:133], v11 offset:17024
	ds_read_b128 v[134:137], v11 offset:17040
	s_waitcnt vmcnt(28) lgkmcnt(1)
	v_pk_mul_f32 v[98:99], v[98:99], v[130:131]
	v_pk_mul_f32 v[100:101], v[100:101], v[132:133]
	ds_write_b32 v13, v98 offset:8320
	ds_write_b32 v13, v99 offset:8580
	ds_write_b32 v13, v100 offset:8840
	ds_write_b32 v13, v101 offset:9100
	ds_read_b128 v[130:133], v11 offset:17056
	s_waitcnt vmcnt(24) lgkmcnt(1)
	v_pk_mul_f32 v[102:103], v[102:103], v[134:135]
	v_pk_mul_f32 v[104:105], v[104:105], v[136:137]
	ds_write_b32 v13, v102 offset:9360
	ds_write_b32 v13, v103 offset:9620
	ds_write_b32 v13, v104 offset:9880
	ds_write_b32 v13, v105 offset:10140
	ds_read_b128 v[134:137], v11 offset:17072
	s_waitcnt vmcnt(20) lgkmcnt(1)
	v_pk_mul_f32 v[106:107], v[106:107], v[130:131]
	v_pk_mul_f32 v[108:109], v[108:109], v[132:133]
	ds_write_b32 v13, v106 offset:10400
	ds_write_b32 v13, v107 offset:10660
	ds_write_b32 v13, v108 offset:10920
	ds_write_b32 v13, v109 offset:11180
	ds_read_b128 v[130:133], v11 offset:17088
	s_waitcnt vmcnt(16) lgkmcnt(1)
; __device__ __forceinline__ unsigned pk2(float lo, float hi) { return pg8::cvt_pk_bf16(lo, hi); }
; template <bool SRC_BF16> __device__ __forceinline__ void tr_tile(const void* src, int stride, int col0, int myrow, float myscale, bf16_t* dst, float* wl, int lane) {
;     ...
;     asm volatile("s_waitcnt vmcnt(0) lgkmcnt(0)" ::: "memory");
;     const int pb = lane & 7, cl = lane >> 3, ib = 32 * (pb >> 2) + 16 * ((pb >> 1) & 1) + 4 * (pb & 1);
; #pragma unroll
;     for (int k = 0; k < 8; ++k) { const int j = cl + 8 * k; float v[8];
; #pragma unroll
;         for (int jj = 0; jj < 8; ++jj) v[jj] = scr[(ib + 8 * (jj >> 2) + (jj & 3)) * 65 + j];
;         u32x4 w; w.x = pk2(v[0], v[1]); w.y = pk2(v[2], v[3]); w.z = pk2(v[4], v[5]); w.w = pk2(v[6], v[7]);
;         *(u32x4*)(dst + (size_t)j * KVL + 8 * pb) = w; }
	v_pk_mul_f32 v[110:111], v[110:111], v[134:135]
	v_pk_mul_f32 v[112:113], v[112:113], v[136:137]
	ds_write_b32 v13, v110 offset:11440
	ds_write_b32 v13, v111 offset:11700
	ds_write_b32 v13, v112 offset:11960
	ds_write_b32 v13, v113 offset:12220
	ds_read_b128 v[134:137], v11 offset:17104
	s_waitcnt vmcnt(12) lgkmcnt(1)
	v_pk_mul_f32 v[114:115], v[114:115], v[130:131]
	v_pk_mul_f32 v[116:117], v[116:117], v[132:133]
	ds_write_b32 v13, v114 offset:12480
	ds_write_b32 v13, v115 offset:12740
	ds_write_b32 v13, v116 offset:13000
	ds_write_b32 v13, v117 offset:13260
	ds_read_b128 v[130:133], v11 offset:17120
	s_waitcnt vmcnt(8) lgkmcnt(1)
	v_pk_mul_f32 v[118:119], v[118:119], v[134:135]
	v_pk_mul_f32 v[120:121], v[120:121], v[136:137]
	ds_write_b32 v13, v118 offset:13520
	ds_write_b32 v13, v119 offset:13780
	ds_write_b32 v13, v120 offset:14040
	ds_write_b32 v13, v121 offset:14300
	ds_read_b128 v[134:137], v11 offset:17136
	s_waitcnt vmcnt(4) lgkmcnt(1)
	v_pk_mul_f32 v[122:123], v[122:123], v[130:131]
	v_pk_mul_f32 v[124:125], v[124:125], v[132:133]
	ds_write_b32 v13, v122 offset:14560
	ds_write_b32 v13, v123 offset:14820
	ds_write_b32 v13, v124 offset:15080
	ds_write_b32 v13, v125 offset:15340
	s_waitcnt vmcnt(0) lgkmcnt(0)
	v_pk_mul_f32 v[126:127], v[126:127], v[134:135]
	v_pk_mul_f32 v[128:129], v[128:129], v[136:137]
	ds_write_b32 v13, v126 offset:15600
	ds_write_b32 v13, v127 offset:15860
	ds_write_b32 v13, v128 offset:16120
	ds_write_b32 v13, v129 offset:16380
	s_waitcnt vmcnt(0) lgkmcnt(0)
	v_add_u32_e32 v19, 0x800, v15
	v_mad_i32_i24 v3, v29, s66, v3
	ds_read2_b32 v[28:29], v15 offset0:65 offset1:73
	ds_read2_b32 v[30:31], v15 offset1:8
	ds_read2_b32 v[32:33], v15 offset0:130 offset1:138
	ds_read2_b32 v[34:35], v15 offset0:195 offset1:203
	ds_read2_b32 v[36:37], v19 offset0:8 offset1:16
	ds_read2_b32 v[38:39], v19 offset0:73 offset1:81
	ds_read2_b32 v[40:41], v19 offset0:138 offset1:146
	ds_read2_b32 v[42:43], v19 offset0:203 offset1:211
	v_lshl_add_u64 v[2:3], v[26:27], 1, v[2:3]
	v_lshlrev_b32_e32 v0, 1, v8
	v_lshl_add_u64 v[26:27], v[2:3], 0, v[0:1]
	v_lshlrev_b32_e32 v0, 1, v10
	v_lshl_add_u64 v[44:45], v[26:27], 0, v[0:1]
	s_mov_b32 s0, 0x11000
	s_waitcnt lgkmcnt(6)
	v_cvt_pk_bf16_f32 v2, v30, v28
	s_waitcnt lgkmcnt(4)
	v_cvt_pk_bf16_f32 v3, v32, v34
	s_waitcnt lgkmcnt(2)
	v_cvt_pk_bf16_f32 v4, v36, v38
	s_waitcnt lgkmcnt(0)
	v_cvt_pk_bf16_f32 v5, v40, v42
	v_add_co_u32_e32 v28, vcc, s0, v44
	global_store_dwordx4 v[44:45], v[2:5], off
	v_lshlrev_b32_e32 v0, 1, v12
	s_nop 0
	v_cvt_pk_bf16_f32 v2, v31, v29
	v_cvt_pk_bf16_f32 v3, v33, v35
	v_cvt_pk_bf16_f32 v4, v37, v39
	v_cvt_pk_bf16_f32 v5, v41, v43
	v_addc_co_u32_e32 v29, vcc, 0, v45, vcc
	global_store_dwordx4 v[28:29], v[2:5], off
	ds_read2_b32 v[28:29], v15 offset0:81 offset1:89
	ds_read2_b32 v[30:31], v15 offset0:16 offset1:24
	ds_read2_b32 v[32:33], v15 offset0:146 offset1:154
	ds_read2_b32 v[34:35], v15 offset0:211 offset1:219
	ds_read2_b32 v[36:37], v19 offset0:24 offset1:32
	ds_read2_b32 v[38:39], v19 offset0:89 offset1:97
	ds_read2_b32 v[40:41], v19 offset0:154 offset1:162
	ds_read2_b32 v[42:43], v19 offset0:219 offset1:227
	v_add_co_u32_e32 v46, vcc, s60, v44
	s_waitcnt lgkmcnt(6)
	v_cvt_pk_bf16_f32 v2, v30, v28
	v_addc_co_u32_e32 v47, vcc, 0, v45, vcc
	s_waitcnt lgkmcnt(4)
	v_cvt_pk_bf16_f32 v3, v32, v34
	s_waitcnt lgkmcnt(2)
	v_cvt_pk_bf16_f32 v4, v36, v38
	s_waitcnt lgkmcnt(0)
	v_cvt_pk_bf16_f32 v5, v40, v42
	v_add_co_u32_e32 v28, vcc, s25, v44
	global_store_dwordx4 v[46:47], v[2:5], off
	s_nop 1
	v_cvt_pk_bf16_f32 v2, v31, v29
	v_cvt_pk_bf16_f32 v3, v33, v35
	v_cvt_pk_bf16_f32 v4, v37, v39
	v_cvt_pk_bf16_f32 v5, v41, v43
	v_addc_co_u32_e32 v29, vcc, 0, v45, vcc
	global_store_dwordx4 v[28:29], v[2:5], off
	ds_read2_b32 v[28:29], v15 offset0:97 offset1:105
	ds_read2_b32 v[30:31], v15 offset0:32 offset1:40
	ds_read2_b32 v[32:33], v15 offset0:162 offset1:170
	ds_read2_b32 v[34:35], v15 offset0:227 offset1:235
	ds_read2_b32 v[36:37], v19 offset0:40 offset1:48
	ds_read2_b32 v[38:39], v19 offset0:105 offset1:113
	ds_read2_b32 v[40:41], v19 offset0:170 offset1:178
	ds_read2_b32 v[42:43], v19 offset0:235 offset1:243
	s_waitcnt lgkmcnt(6)
	v_cvt_pk_bf16_f32 v2, v30, v28
	s_waitcnt lgkmcnt(4)
	v_cvt_pk_bf16_f32 v3, v32, v34
	s_waitcnt lgkmcnt(2)
	v_cvt_pk_bf16_f32 v4, v36, v38
	v_lshl_add_u64 v[44:45], v[26:27], 0, v[0:1]
	s_waitcnt lgkmcnt(0)
	v_cvt_pk_bf16_f32 v5, v40, v42
	v_lshlrev_b32_e32 v0, 1, v14
	global_store_dwordx4 v[44:45], v[2:5], off
	s_nop 1
	v_cvt_pk_bf16_f32 v2, v31, v29
	v_cvt_pk_bf16_f32 v3, v33, v35
	v_cvt_pk_bf16_f32 v4, v37, v39
	v_cvt_pk_bf16_f32 v5, v41, v43
	v_lshl_add_u64 v[28:29], v[26:27], 0, v[0:1]
	global_store_dwordx4 v[28:29], v[2:5], off
	v_add_u32_e32 v0, 0xa00, v15
	ds_read2_b32 v[28:29], v15 offset0:48 offset1:56
	ds_read2_b32 v[30:31], v15 offset0:113 offset1:121
	ds_read2_b32 v[32:33], v15 offset0:178 offset1:186
	ds_read2_b32 v[34:35], v15 offset0:243 offset1:251
	ds_read2_b32 v[36:37], v19 offset0:56 offset1:64
	ds_read2_b32 v[38:39], v19 offset0:121 offset1:129
	ds_read2_b32 v[40:41], v19 offset0:186 offset1:194
	ds_read2_b32 v[42:43], v0 offset0:123 offset1:131
	v_lshlrev_b32_e32 v0, 1, v16
	s_waitcnt lgkmcnt(6)
	v_cvt_pk_bf16_f32 v2, v28, v30
	s_waitcnt lgkmcnt(4)
	v_cvt_pk_bf16_f32 v3, v32, v34
	s_waitcnt lgkmcnt(2)
	v_cvt_pk_bf16_f32 v4, v36, v38
	s_waitcnt lgkmcnt(0)
	v_cvt_pk_bf16_f32 v5, v40, v42
	v_lshl_add_u64 v[44:45], v[26:27], 0, v[0:1]
	v_lshlrev_b32_e32 v0, 1, v18
	global_store_dwordx4 v[44:45], v[2:5], off
	v_lshl_add_u64 v[26:27], v[26:27], 0, v[0:1]
	s_nop 0
	v_cvt_pk_bf16_f32 v2, v29, v31
	v_cvt_pk_bf16_f32 v3, v33, v35
	v_cvt_pk_bf16_f32 v4, v37, v39
	v_cvt_pk_bf16_f32 v5, v41, v43
	global_store_dwordx4 v[26:27], v[2:5], off
	s_waitcnt lgkmcnt(0)

; __device__ __forceinline__ float bf2f(unsigned v) { return __uint_as_float(v << 16); }
; template <bool SRC_BF16> __device__ __forceinline__ void tr_tile(const void* src, int stride, int col0, int myrow, float myscale, bf16_t* dst, float* wl, int lane) {
;     ...
;     for (int i = 0; i < 64; ++i) { const int r = rws[i]; float v;
;         if (SRC_BF16) v = bf2f(((const bf16_t*)src)[(size_t)r * stride + col0 + lane]); else v = ((const float*)src)[(size_t)r * stride + col0 + lane] * scs[i];
;         scr[i * 65 + lane] = v; }
; __device__ __forceinline__ void prep2_phase(const Args& a, float* lds) {
;     ...
;           } else { const int t2 = tI - 4 * 16 * 68; const int pt = t2 % 68, rest = t2 / 68, nh = rest & 1, bdg = rest >> 1, g = bdg & 1, dir = (bdg >> 1) & 1, b = bdg >> 2;
;               tr_tile<false>(xbc, 1536, 1024 + g * 128 + 64 * nh, seq_row(b, dir, 64 * pt + lane), 1.f, BT + ((size_t)bdg * 128 + 64 * nh) * KVL + 64 * pt, wl, lane); }
.LBB0_315:
	s_movk_i32 s0, 0x10ff
	v_cmp_lt_i32_e32 vcc, s0, v9
	s_and_saveexec_b64 s[0:1], vcc
	s_xor_b64 s[8:9], exec, s[0:1]
	s_cbranch_execz .LBB0_321
	v_add_u16_e32 v0, 0xef00, v9
	v_mul_u32_u24_e32 v3, 0xf0f1, v0
	v_lshrrev_b32_e32 v2, 22, v3
	v_mul_lo_u16_e32 v4, 0x44, v2
	v_sub_u16_e32 v4, v0, v4
	v_lshlrev_b16_e32 v19, 6, v4
	v_cmp_lt_u16_e64 s[0:1], 3, v4
	v_and_b32_e32 v4, 4, v2
	v_lshrrev_b32_e32 v0, 25, v3
	v_or_b32_e32 v3, v6, v19
	v_cmp_eq_u32_e32 vcc, 0, v4
	s_and_saveexec_b64 s[14:15], s[0:1]
	s_xor_b64 s[0:1], exec, s[14:15]
	v_add_u32_e32 v4, 0xffffff00, v3
	v_sub_u32_e32 v3, 0x10ff, v3
	v_cndmask_b32_e32 v3, v3, v4, vcc
	v_lshl_add_u32 v4, v0, 12, v3
	s_andn2_saveexec_b64 s[0:1], s[0:1]
	v_sub_u32_e32 v4, 0xff, v3
	v_lshlrev_b32_e32 v0, 8, v0
	v_cndmask_b32_e32 v3, v4, v3, vcc
	v_add3_u32 v4, v0, v3, s70
	s_or_b64 exec, exec, s[0:1]
	v_lshlrev_b32_e32 v0, 8, v2
	v_and_b32_e32 v0, 0x300, v0
	ds_write2st64_b32 v13, v4, v195 offset0:65 offset1:66
	v_lshl_add_u64 v[4:5], s[26:27], 0, v[0:1]
	v_mov_b32_e32 v25, v1
	s_waitcnt lgkmcnt(0)
	v_lshl_add_u64 v[4:5], v[4:5], 0, v[24:25]
	s_mov_b64 s[0:1], 0x1000
	v_lshl_add_u64 v[26:27], v[4:5], 0, s[0:1]
	v_mul_u32_u24_e32 v0, 0x88000, v2
	ds_read_b128 v[2:5], v11 offset:16640
	ds_read_b128 v[28:31], v11 offset:16656
	s_waitcnt lgkmcnt(0)
	v_mad_i64_i32 v[32:33], s[0:1], v2, s78, v[26:27]
	v_mad_i64_i32 v[2:3], s[0:1], v3, s78, v[26:27]
	global_load_dword v66, v[32:33], off
	global_load_dword v67, v[2:3], off
	s_waitcnt lgkmcnt(0)
	v_mad_i64_i32 v[2:3], s[0:1], v4, s78, v[26:27]
	v_mad_i64_i32 v[4:5], s[0:1], v5, s78, v[26:27]
	global_load_dword v68, v[2:3], off
	s_nop 0
	global_load_dword v69, v[4:5], off
	v_mad_i64_i32 v[4:5], s[0:1], v29, s78, v[26:27]
	v_mad_i64_i32 v[2:3], s[0:1], v28, s78, v[26:27]
	global_load_dword v70, v[2:3], off
	global_load_dword v71, v[4:5], off
	s_waitcnt lgkmcnt(0)
	v_mad_i64_i32 v[2:3], s[0:1], v30, s78, v[26:27]
	v_mad_i64_i32 v[28:29], s[0:1], v31, s78, v[26:27]
	global_load_dword v72, v[2:3], off
	s_nop 0
	global_load_dword v73, v[28:29], off
	ds_read_b128 v[2:5], v11 offset:16672
	ds_read_b128 v[28:31], v11 offset:16688
	s_waitcnt lgkmcnt(0)
	v_mad_i64_i32 v[32:33], s[0:1], v2, s78, v[26:27]
	v_mad_i64_i32 v[2:3], s[0:1], v3, s78, v[26:27]
	global_load_dword v74, v[32:33], off
	global_load_dword v75, v[2:3], off
	s_waitcnt lgkmcnt(0)
	v_mad_i64_i32 v[2:3], s[0:1], v4, s78, v[26:27]
	v_mad_i64_i32 v[4:5], s[0:1], v5, s78, v[26:27]
	global_load_dword v76, v[2:3], off
	s_nop 0
	global_load_dword v77, v[4:5], off
	v_mad_i64_i32 v[4:5], s[0:1], v29, s78, v[26:27]
	v_mad_i64_i32 v[2:3], s[0:1], v28, s78, v[26:27]
	global_load_dword v78, v[2:3], off
	global_load_dword v79, v[4:5], off
	s_waitcnt lgkmcnt(0)
	v_mad_i64_i32 v[2:3], s[0:1], v30, s78, v[26:27]
	v_mad_i64_i32 v[28:29], s[0:1], v31, s78, v[26:27]
	global_load_dword v80, v[2:3], off
	s_nop 0
	global_load_dword v81, v[28:29], off
	ds_read_b128 v[2:5], v11 offset:16704
	ds_read_b128 v[28:31], v11 offset:16720
	s_waitcnt lgkmcnt(0)
	v_mad_i64_i32 v[32:33], s[0:1], v2, s78, v[26:27]
	v_mad_i64_i32 v[2:3], s[0:1], v3, s78, v[26:27]
	global_load_dword v82, v[32:33], off
	global_load_dword v83, v[2:3], off
	s_waitcnt lgkmcnt(0)
	v_mad_i64_i32 v[2:3], s[0:1], v4, s78, v[26:27]
	v_mad_i64_i32 v[4:5], s[0:1], v5, s78, v[26:27]
	global_load_dword v84, v[2:3], off
	s_nop 0
	global_load_dword v85, v[4:5], off
	v_mad_i64_i32 v[4:5], s[0:1], v29, s78, v[26:27]
	v_mad_i64_i32 v[2:3], s[0:1], v28, s78, v[26:27]
	global_load_dword v86, v[2:3], off
	global_load_dword v87, v[4:5], off
	s_waitcnt lgkmcnt(0)
	v_mad_i64_i32 v[2:3], s[0:1], v30, s78, v[26:27]
	v_mad_i64_i32 v[28:29], s[0:1], v31, s78, v[26:27]
	global_load_dword v88, v[2:3], off
	s_nop 0
	global_load_dword v89, v[28:29], off
	ds_read_b128 v[2:5], v11 offset:16736
	s_waitcnt lgkmcnt(0)
	v_mad_i64_i32 v[28:29], s[0:1], v2, s78, v[26:27]
	v_mad_i64_i32 v[2:3], s[0:1], v3, s78, v[26:27]
	global_load_dword v90, v[28:29], off
	global_load_dword v91, v[2:3], off
	s_waitcnt lgkmcnt(0)
	v_mad_i64_i32 v[2:3], s[0:1], v4, s78, v[26:27]
	v_mad_i64_i32 v[4:5], s[0:1], v5, s78, v[26:27]
	global_load_dword v92, v[2:3], off
	s_nop 0
	global_load_dword v93, v[4:5], off
	ds_read_b128 v[2:5], v11 offset:16752
	s_waitcnt lgkmcnt(0)
	v_mad_i64_i32 v[28:29], s[0:1], v2, s78, v[26:27]
	v_mad_i64_i32 v[2:3], s[0:1], v3, s78, v[26:27]
	global_load_dword v94, v[28:29], off
	global_load_dword v95, v[2:3], off
	s_waitcnt lgkmcnt(0)
	v_mad_i64_i32 v[2:3], s[0:1], v4, s78, v[26:27]
	v_mad_i64_i32 v[4:5], s[0:1], v5, s78, v[26:27]
	global_load_dword v96, v[2:3], off
	s_nop 0
	global_load_dword v97, v[4:5], off
	ds_read_b128 v[2:5], v11 offset:16768
	s_waitcnt lgkmcnt(0)
	v_mad_i64_i32 v[28:29], s[0:1], v2, s78, v[26:27]
	v_mad_i64_i32 v[2:3], s[0:1], v3, s78, v[26:27]
	ds_read_b128 v[130:133], v11 offset:16896
	ds_read_b128 v[134:137], v11 offset:16912
	s_waitcnt vmcnt(28) lgkmcnt(1)
	v_pk_mul_f32 v[66:67], v[66:67], v[130:131]
	v_pk_mul_f32 v[68:69], v[68:69], v[132:133]
	ds_write_b32 v13, v66 offset:0
	ds_write_b32 v13, v67 offset:260
	ds_write_b32 v13, v68 offset:520
	ds_write_b32 v13, v69 offset:780
	ds_read_b128 v[130:133], v11 offset:16928
	s_waitcnt vmcnt(24) lgkmcnt(1)
	v_pk_mul_f32 v[70:71], v[70:71], v[134:135]
	v_pk_mul_f32 v[72:73], v[72:73], v[136:137]
	ds_write_b32 v13, v70 offset:1040
	ds_write_b32 v13, v71 offset:1300
	ds_write_b32 v13, v72 offset:1560
	ds_write_b32 v13, v73 offset:1820
	ds_read_b128 v[134:137], v11 offset:16944
	s_waitcnt vmcnt(20) lgkmcnt(1)
; __device__ __forceinline__ float bf2f(unsigned v) { return __uint_as_float(v << 16); }
; template <bool SRC_BF16> __device__ __forceinline__ void tr_tile(const void* src, int stride, int col0, int myrow, float myscale, bf16_t* dst, float* wl, int lane) {
;     ...
; #pragma unroll 32
;     for (int i = 0; i < 64; ++i) { const int r = rws[i]; float v;
;         if (SRC_BF16) v = bf2f(((const bf16_t*)src)[(size_t)r * stride + col0 + lane]); else v = ((const float*)src)[(size_t)r * stride + col0 + lane] * scs[i];
;         scr[i * 65 + lane] = v; }
;     asm volatile("s_waitcnt vmcnt(0) lgkmcnt(0)" ::: "memory");
	v_pk_mul_f32 v[74:75], v[74:75], v[130:131]
	v_pk_mul_f32 v[76:77], v[76:77], v[132:133]
	ds_write_b32 v13, v74 offset:2080
	ds_write_b32 v13, v75 offset:2340
	ds_write_b32 v13, v76 offset:2600
	ds_write_b32 v13, v77 offset:2860
	ds_read_b128 v[130:133], v11 offset:16960
	s_waitcnt vmcnt(16) lgkmcnt(1)
	v_pk_mul_f32 v[78:79], v[78:79], v[134:135]
	v_pk_mul_f32 v[80:81], v[80:81], v[136:137]
	ds_write_b32 v13, v78 offset:3120
	ds_write_b32 v13, v79 offset:3380
	ds_write_b32 v13, v80 offset:3640
	ds_write_b32 v13, v81 offset:3900
	ds_read_b128 v[134:137], v11 offset:16976
	s_waitcnt vmcnt(12) lgkmcnt(1)
	v_pk_mul_f32 v[82:83], v[82:83], v[130:131]
	v_pk_mul_f32 v[84:85], v[84:85], v[132:133]
	ds_write_b32 v13, v82 offset:4160
	ds_write_b32 v13, v83 offset:4420
	ds_write_b32 v13, v84 offset:4680
	ds_write_b32 v13, v85 offset:4940
	ds_read_b128 v[130:133], v11 offset:16992
	s_waitcnt vmcnt(8) lgkmcnt(1)
	v_pk_mul_f32 v[86:87], v[86:87], v[134:135]
	v_pk_mul_f32 v[88:89], v[88:89], v[136:137]
	ds_write_b32 v13, v86 offset:5200
	ds_write_b32 v13, v87 offset:5460
	ds_write_b32 v13, v88 offset:5720
	ds_write_b32 v13, v89 offset:5980
	ds_read_b128 v[134:137], v11 offset:17008
	s_waitcnt vmcnt(4) lgkmcnt(1)
	v_pk_mul_f32 v[90:91], v[90:91], v[130:131]
	v_pk_mul_f32 v[92:93], v[92:93], v[132:133]
	ds_write_b32 v13, v90 offset:6240
	ds_write_b32 v13, v91 offset:6500
	ds_write_b32 v13, v92 offset:6760
	ds_write_b32 v13, v93 offset:7020
	s_waitcnt vmcnt(0) lgkmcnt(0)
	v_pk_mul_f32 v[94:95], v[94:95], v[134:135]
	v_pk_mul_f32 v[96:97], v[96:97], v[136:137]
	ds_write_b32 v13, v94 offset:7280
	ds_write_b32 v13, v95 offset:7540
	ds_write_b32 v13, v96 offset:7800
	ds_write_b32 v13, v97 offset:8060
	s_waitcnt lgkmcnt(0)
	global_load_dword v98, v[28:29], off
	global_load_dword v99, v[2:3], off
	s_waitcnt lgkmcnt(0)
	v_mad_i64_i32 v[2:3], s[0:1], v4, s78, v[26:27]
	v_mad_i64_i32 v[4:5], s[0:1], v5, s78, v[26:27]
	global_load_dword v100, v[2:3], off
	s_nop 0
	global_load_dword v101, v[4:5], off
	ds_read_b128 v[2:5], v11 offset:16784
	s_waitcnt lgkmcnt(0)
	v_mad_i64_i32 v[28:29], s[0:1], v2, s78, v[26:27]
	v_mad_i64_i32 v[2:3], s[0:1], v3, s78, v[26:27]
	global_load_dword v102, v[28:29], off
	global_load_dword v103, v[2:3], off
	s_waitcnt lgkmcnt(0)
	v_mad_i64_i32 v[2:3], s[0:1], v4, s78, v[26:27]
	v_mad_i64_i32 v[4:5], s[0:1], v5, s78, v[26:27]
	global_load_dword v104, v[2:3], off
	s_nop 0
	global_load_dword v105, v[4:5], off
	ds_read_b128 v[2:5], v11 offset:16800
	s_waitcnt lgkmcnt(0)
	v_mad_i64_i32 v[28:29], s[0:1], v2, s78, v[26:27]
	v_mad_i64_i32 v[2:3], s[0:1], v3, s78, v[26:27]
	global_load_dword v106, v[28:29], off
	global_load_dword v107, v[2:3], off
	s_waitcnt lgkmcnt(0)
	v_mad_i64_i32 v[2:3], s[0:1], v4, s78, v[26:27]
	v_mad_i64_i32 v[4:5], s[0:1], v5, s78, v[26:27]
	global_load_dword v108, v[2:3], off
	s_nop 0
	global_load_dword v109, v[4:5], off
	ds_read_b128 v[2:5], v11 offset:16816
	s_waitcnt lgkmcnt(0)
	v_mad_i64_i32 v[28:29], s[0:1], v2, s78, v[26:27]
	v_mad_i64_i32 v[2:3], s[0:1], v3, s78, v[26:27]
	global_load_dword v110, v[28:29], off
	global_load_dword v111, v[2:3], off
	s_waitcnt lgkmcnt(0)
	v_mad_i64_i32 v[2:3], s[0:1], v4, s78, v[26:27]
	v_mad_i64_i32 v[4:5], s[0:1], v5, s78, v[26:27]
	global_load_dword v112, v[2:3], off
	s_nop 0
	global_load_dword v113, v[4:5], off
	ds_read_b128 v[2:5], v11 offset:16832
	s_waitcnt lgkmcnt(0)
	v_mad_i64_i32 v[28:29], s[0:1], v2, s78, v[26:27]
	v_mad_i64_i32 v[2:3], s[0:1], v3, s78, v[26:27]
	global_load_dword v114, v[28:29], off
	global_load_dword v115, v[2:3], off
	s_waitcnt lgkmcnt(0)
	v_mad_i64_i32 v[2:3], s[0:1], v4, s78, v[26:27]
	v_mad_i64_i32 v[4:5], s[0:1], v5, s78, v[26:27]
	global_load_dword v116, v[2:3], off
	s_nop 0
	global_load_dword v117, v[4:5], off
	ds_read_b128 v[2:5], v11 offset:16848
	s_waitcnt lgkmcnt(0)
	v_mad_i64_i32 v[28:29], s[0:1], v2, s78, v[26:27]
	v_mad_i64_i32 v[2:3], s[0:1], v3, s78, v[26:27]
	global_load_dword v118, v[28:29], off
	global_load_dword v119, v[2:3], off
	s_waitcnt lgkmcnt(0)
	v_mad_i64_i32 v[2:3], s[0:1], v4, s78, v[26:27]
	v_mad_i64_i32 v[4:5], s[0:1], v5, s78, v[26:27]
	global_load_dword v120, v[2:3], off
	s_nop 0
	global_load_dword v121, v[4:5], off
	ds_read_b128 v[2:5], v11 offset:16864
	s_waitcnt lgkmcnt(0)
	v_mad_i64_i32 v[28:29], s[0:1], v2, s78, v[26:27]
	v_mad_i64_i32 v[2:3], s[0:1], v3, s78, v[26:27]
	global_load_dword v122, v[28:29], off
	global_load_dword v123, v[2:3], off
	s_waitcnt lgkmcnt(0)
	v_mad_i64_i32 v[2:3], s[0:1], v4, s78, v[26:27]
	v_mad_i64_i32 v[4:5], s[0:1], v5, s78, v[26:27]
	global_load_dword v124, v[2:3], off
	s_nop 0
	global_load_dword v125, v[4:5], off
	ds_read_b128 v[28:31], v11 offset:16880
	s_waitcnt lgkmcnt(0)
	v_mad_i64_i32 v[2:3], s[0:1], v28, s78, v[26:27]
	v_mad_i64_i32 v[4:5], s[0:1], v29, s78, v[26:27]
	global_load_dword v126, v[2:3], off
	global_load_dword v127, v[4:5], off
	s_waitcnt lgkmcnt(0)
	v_mad_i64_i32 v[2:3], s[0:1], v30, s78, v[26:27]
	v_mad_i64_i32 v[26:27], s[0:1], v31, s78, v[26:27]
	global_load_dword v128, v[2:3], off
	s_nop 0
	global_load_dword v129, v[26:27], off
	s_mov_b32 s0, 0x11000
	v_lshl_add_u64 v[2:3], s[30:31], 0, v[0:1]
	v_lshlrev_b32_e32 v0, 1, v19
	ds_read_b128 v[130:133], v11 offset:17024
	ds_read_b128 v[134:137], v11 offset:17040
	s_waitcnt vmcnt(28) lgkmcnt(1)
	v_pk_mul_f32 v[98:99], v[98:99], v[130:131]
	v_pk_mul_f32 v[100:101], v[100:101], v[132:133]
	ds_write_b32 v13, v98 offset:8320
	ds_write_b32 v13, v99 offset:8580
	ds_write_b32 v13, v100 offset:8840
	ds_write_b32 v13, v101 offset:9100
	ds_read_b128 v[130:133], v11 offset:17056
	s_waitcnt vmcnt(24) lgkmcnt(1)
; __device__ __forceinline__ unsigned pk2(float lo, float hi) { return pg8::cvt_pk_bf16(lo, hi); }
; template <bool SRC_BF16> __device__ __forceinline__ void tr_tile(const void* src, int stride, int col0, int myrow, float myscale, bf16_t* dst, float* wl, int lane) {
;     ...
;         scr[i * 65 + lane] = v; }
;     asm volatile("s_waitcnt vmcnt(0) lgkmcnt(0)" ::: "memory");
;     const int pb = lane & 7, cl = lane >> 3, ib = 32 * (pb >> 2) + 16 * ((pb >> 1) & 1) + 4 * (pb & 1);
; #pragma unroll
;     for (int k = 0; k < 8; ++k) { const int j = cl + 8 * k; float v[8];
; #pragma unroll
;         for (int jj = 0; jj < 8; ++jj) v[jj] = scr[(ib + 8 * (jj >> 2) + (jj & 3)) * 65 + j];
;         u32x4 w; w.x = pk2(v[0], v[1]); w.y = pk2(v[2], v[3]); w.z = pk2(v[4], v[5]); w.w = pk2(v[6], v[7]);
;         *(u32x4*)(dst + (size_t)j * KVL + 8 * pb) = w; }
;     asm volatile("s_waitcnt lgkmcnt(0)" ::: "memory");
	v_pk_mul_f32 v[102:103], v[102:103], v[134:135]
	v_pk_mul_f32 v[104:105], v[104:105], v[136:137]
	ds_write_b32 v13, v102 offset:9360
	ds_write_b32 v13, v103 offset:9620
	ds_write_b32 v13, v104 offset:9880
	ds_write_b32 v13, v105 offset:10140
	ds_read_b128 v[134:137], v11 offset:17072
	s_waitcnt vmcnt(20) lgkmcnt(1)
	v_pk_mul_f32 v[106:107], v[106:107], v[130:131]
	v_pk_mul_f32 v[108:109], v[108:109], v[132:133]
	ds_write_b32 v13, v106 offset:10400
	ds_write_b32 v13, v107 offset:10660
	ds_write_b32 v13, v108 offset:10920
	ds_write_b32 v13, v109 offset:11180
	ds_read_b128 v[130:133], v11 offset:17088
	s_waitcnt vmcnt(16) lgkmcnt(1)
	v_pk_mul_f32 v[110:111], v[110:111], v[134:135]
	v_pk_mul_f32 v[112:113], v[112:113], v[136:137]
	ds_write_b32 v13, v110 offset:11440
	ds_write_b32 v13, v111 offset:11700
	ds_write_b32 v13, v112 offset:11960
	ds_write_b32 v13, v113 offset:12220
	ds_read_b128 v[134:137], v11 offset:17104
	s_waitcnt vmcnt(12) lgkmcnt(1)
	v_pk_mul_f32 v[114:115], v[114:115], v[130:131]
	v_pk_mul_f32 v[116:117], v[116:117], v[132:133]
	ds_write_b32 v13, v114 offset:12480
	ds_write_b32 v13, v115 offset:12740
	ds_write_b32 v13, v116 offset:13000
	ds_write_b32 v13, v117 offset:13260
	ds_read_b128 v[130:133], v11 offset:17120
	s_waitcnt vmcnt(8) lgkmcnt(1)
	v_pk_mul_f32 v[118:119], v[118:119], v[134:135]
	v_pk_mul_f32 v[120:121], v[120:121], v[136:137]
	ds_write_b32 v13, v118 offset:13520
	ds_write_b32 v13, v119 offset:13780
	ds_write_b32 v13, v120 offset:14040
	ds_write_b32 v13, v121 offset:14300
	ds_read_b128 v[134:137], v11 offset:17136
	s_waitcnt vmcnt(4) lgkmcnt(1)
	v_pk_mul_f32 v[122:123], v[122:123], v[130:131]
	v_pk_mul_f32 v[124:125], v[124:125], v[132:133]
	ds_write_b32 v13, v122 offset:14560
	ds_write_b32 v13, v123 offset:14820
	ds_write_b32 v13, v124 offset:15080
	ds_write_b32 v13, v125 offset:15340
	s_waitcnt vmcnt(0) lgkmcnt(0)
	v_pk_mul_f32 v[126:127], v[126:127], v[134:135]
	v_pk_mul_f32 v[128:129], v[128:129], v[136:137]
	ds_write_b32 v13, v126 offset:15600
	ds_write_b32 v13, v127 offset:15860
	ds_write_b32 v13, v128 offset:16120
	ds_write_b32 v13, v129 offset:16380
	s_waitcnt vmcnt(0) lgkmcnt(0)
	v_add_u32_e32 v19, 0x800, v15
	ds_read2_b32 v[28:29], v15 offset0:65 offset1:73
	ds_read2_b32 v[30:31], v15 offset1:8
	ds_read2_b32 v[32:33], v15 offset0:130 offset1:138
	ds_read2_b32 v[34:35], v15 offset0:195 offset1:203
	ds_read2_b32 v[36:37], v19 offset0:8 offset1:16
	ds_read2_b32 v[38:39], v19 offset0:73 offset1:81
	ds_read2_b32 v[40:41], v19 offset0:138 offset1:146
	ds_read2_b32 v[42:43], v19 offset0:203 offset1:211
	v_lshl_add_u64 v[2:3], v[2:3], 0, v[0:1]
	v_lshlrev_b32_e32 v0, 1, v8
	v_lshl_add_u64 v[26:27], v[2:3], 0, v[0:1]
	v_lshlrev_b32_e32 v0, 1, v10
	v_lshl_add_u64 v[44:45], v[26:27], 0, v[0:1]
	s_waitcnt lgkmcnt(6)
	v_cvt_pk_bf16_f32 v2, v30, v28
	s_waitcnt lgkmcnt(4)
	v_cvt_pk_bf16_f32 v3, v32, v34
	s_waitcnt lgkmcnt(2)
	v_cvt_pk_bf16_f32 v4, v36, v38
	s_waitcnt lgkmcnt(0)
	v_cvt_pk_bf16_f32 v5, v40, v42
	v_add_co_u32_e32 v28, vcc, s0, v44
	global_store_dwordx4 v[44:45], v[2:5], off
	v_lshlrev_b32_e32 v0, 1, v12
	s_nop 0
	v_cvt_pk_bf16_f32 v2, v31, v29
	v_cvt_pk_bf16_f32 v3, v33, v35
	v_cvt_pk_bf16_f32 v4, v37, v39
	v_cvt_pk_bf16_f32 v5, v41, v43
	v_addc_co_u32_e32 v29, vcc, 0, v45, vcc
	global_store_dwordx4 v[28:29], v[2:5], off
	ds_read2_b32 v[28:29], v15 offset0:81 offset1:89
	ds_read2_b32 v[30:31], v15 offset0:16 offset1:24
	ds_read2_b32 v[32:33], v15 offset0:146 offset1:154
	ds_read2_b32 v[34:35], v15 offset0:211 offset1:219
	ds_read2_b32 v[36:37], v19 offset0:24 offset1:32
	ds_read2_b32 v[38:39], v19 offset0:89 offset1:97
	ds_read2_b32 v[40:41], v19 offset0:154 offset1:162
	ds_read2_b32 v[42:43], v19 offset0:219 offset1:227
	v_add_co_u32_e32 v46, vcc, s60, v44
	s_waitcnt lgkmcnt(6)
	v_cvt_pk_bf16_f32 v2, v30, v28
	v_addc_co_u32_e32 v47, vcc, 0, v45, vcc
	s_waitcnt lgkmcnt(4)
	v_cvt_pk_bf16_f32 v3, v32, v34
	s_waitcnt lgkmcnt(2)
	v_cvt_pk_bf16_f32 v4, v36, v38
	s_waitcnt lgkmcnt(0)
	v_cvt_pk_bf16_f32 v5, v40, v42
	v_add_co_u32_e32 v28, vcc, s25, v44
	global_store_dwordx4 v[46:47], v[2:5], off
	s_nop 1
	v_cvt_pk_bf16_f32 v2, v31, v29
	v_cvt_pk_bf16_f32 v3, v33, v35
	v_cvt_pk_bf16_f32 v4, v37, v39
	v_cvt_pk_bf16_f32 v5, v41, v43
	v_addc_co_u32_e32 v29, vcc, 0, v45, vcc
	global_store_dwordx4 v[28:29], v[2:5], off
	ds_read2_b32 v[28:29], v15 offset0:97 offset1:105
	ds_read2_b32 v[30:31], v15 offset0:32 offset1:40
	ds_read2_b32 v[32:33], v15 offset0:162 offset1:170
	ds_read2_b32 v[34:35], v15 offset0:227 offset1:235
	ds_read2_b32 v[36:37], v19 offset0:40 offset1:48
	ds_read2_b32 v[38:39], v19 offset0:105 offset1:113
	ds_read2_b32 v[40:41], v19 offset0:170 offset1:178
	ds_read2_b32 v[42:43], v19 offset0:235 offset1:243
	s_waitcnt lgkmcnt(6)
	v_cvt_pk_bf16_f32 v2, v30, v28
	s_waitcnt lgkmcnt(4)
	v_cvt_pk_bf16_f32 v3, v32, v34
	s_waitcnt lgkmcnt(2)
	v_cvt_pk_bf16_f32 v4, v36, v38
	v_lshl_add_u64 v[44:45], v[26:27], 0, v[0:1]
	s_waitcnt lgkmcnt(0)
	v_cvt_pk_bf16_f32 v5, v40, v42
	v_lshlrev_b32_e32 v0, 1, v14
	global_store_dwordx4 v[44:45], v[2:5], off
	s_nop 1
	v_cvt_pk_bf16_f32 v2, v31, v29
	v_cvt_pk_bf16_f32 v3, v33, v35
	v_cvt_pk_bf16_f32 v4, v37, v39
	v_cvt_pk_bf16_f32 v5, v41, v43
	v_lshl_add_u64 v[28:29], v[26:27], 0, v[0:1]
	global_store_dwordx4 v[28:29], v[2:5], off
	v_add_u32_e32 v0, 0xa00, v15
	ds_read2_b32 v[28:29], v15 offset0:48 offset1:56
	ds_read2_b32 v[30:31], v15 offset0:113 offset1:121
	ds_read2_b32 v[32:33], v15 offset0:178 offset1:186
	ds_read2_b32 v[34:35], v15 offset0:243 offset1:251
	ds_read2_b32 v[36:37], v19 offset0:56 offset1:64
	ds_read2_b32 v[38:39], v19 offset0:121 offset1:129
	ds_read2_b32 v[40:41], v19 offset0:186 offset1:194
	ds_read2_b32 v[42:43], v0 offset0:123 offset1:131
	v_lshlrev_b32_e32 v0, 1, v16
	s_waitcnt lgkmcnt(6)
	v_cvt_pk_bf16_f32 v2, v28, v30
	s_waitcnt lgkmcnt(4)
	v_cvt_pk_bf16_f32 v3, v32, v34
	s_waitcnt lgkmcnt(2)
	v_cvt_pk_bf16_f32 v4, v36, v38
	s_waitcnt lgkmcnt(0)
	v_cvt_pk_bf16_f32 v5, v40, v42
	v_lshl_add_u64 v[44:45], v[26:27], 0, v[0:1]
	v_lshlrev_b32_e32 v0, 1, v18
	global_store_dwordx4 v[44:45], v[2:5], off
	v_lshl_add_u64 v[26:27], v[26:27], 0, v[0:1]
	s_nop 0
	v_cvt_pk_bf16_f32 v2, v29, v31
	v_cvt_pk_bf16_f32 v3, v33, v35
	v_cvt_pk_bf16_f32 v4, v37, v39
	v_cvt_pk_bf16_f32 v5, v41, v43
	global_store_dwordx4 v[26:27], v[2:5], off
	s_waitcnt lgkmcnt(0)
